# P8 K-loop fully unrolled (8 copies), each copy carries its own deferred group store, no dispatch tree
# baseline (speedup 1.0000x reference)
.LBB0_877:
	s_cmp_eq_u32 s100, 0
	s_cbranch_scc1 .Ldhs8_idle0
	global_store_dwordx4 v255, v[226:229], s[16:17]
.Ldhs8_done0:
	ds_read_b128 v[150:153], v147
	ds_read_b128 v[154:157], v147 offset:1024
	ds_read_b128 v[158:161], v147 offset:2048
	ds_read_b128 v[162:165], v147 offset:3072
	ds_read_b128 v[166:169], v148
	ds_read_b128 v[170:173], v148 offset:1024
	ds_read_b128 v[174:177], v148 offset:2048
	ds_read_b128 v[178:181], v148 offset:3072
	s_add_u32 s38, s36, 0xfffc0080
	s_addc_u32 s39, s37, -1
	s_cmp_eq_u32 s61, 12
	s_cselect_b32 s41, s27, s39
	s_cselect_b32 s40, s57, s38
	s_cselect_b32 s39, s25, s60
	s_cselect_b32 s38, s58, s59
	v_lshl_add_u64 v[214:215], s[36:37], 0, v[136:137]
	s_add_i32 m0, s35, 0xc000
	ds_read_b128 v[182:185], v149
	ds_read_b128 v[186:189], v149 offset:1024
	ds_read_b128 v[190:193], v149 offset:2048
	ds_read_b128 v[194:197], v149 offset:3072
	ds_read_b128 v[198:201], v149 offset:4096
	ds_read_b128 v[202:205], v149 offset:5120
	ds_read_b128 v[206:209], v149 offset:6144
	ds_read_b128 v[210:213], v149 offset:7168
	global_load_lds_dwordx4 v[214:215], off
	v_lshl_add_u64 v[214:215], s[36:37], 0, v[138:139]
	s_add_i32 m0, s35, 0xe000
	s_nop 0
	global_load_lds_dwordx4 v[214:215], off
	s_waitcnt vmcnt(9)
	s_waitcnt lgkmcnt(0)
	s_barrier
	s_setprio 1
	s_waitcnt lgkmcnt(0)
	v_mfma_f32_16x16x32_bf16 v[124:127], v[150:153], v[182:185], v[124:127]
	v_mfma_f32_16x16x32_bf16 v[120:123], v[158:161], v[182:185], v[120:123]
	v_mfma_f32_16x16x32_bf16 v[108:111], v[150:153], v[190:193], v[108:111]
	v_mfma_f32_16x16x32_bf16 v[104:107], v[158:161], v[190:193], v[104:107]
	v_mfma_f32_16x16x32_bf16 v[92:95], v[150:153], v[198:201], v[92:95]
	v_mfma_f32_16x16x32_bf16 v[88:91], v[158:161], v[198:201], v[88:91]
	v_mfma_f32_16x16x32_bf16 v[76:79], v[150:153], v[206:209], v[76:79]
	v_mfma_f32_16x16x32_bf16 v[72:75], v[158:161], v[206:209], v[72:75]
	v_mfma_f32_16x16x32_bf16 v[124:127], v[154:157], v[186:189], v[124:127]
	v_mfma_f32_16x16x32_bf16 v[120:123], v[162:165], v[186:189], v[120:123]
	v_mfma_f32_16x16x32_bf16 v[108:111], v[154:157], v[194:197], v[108:111]
	v_mfma_f32_16x16x32_bf16 v[104:107], v[162:165], v[194:197], v[104:107]
	v_mfma_f32_16x16x32_bf16 v[92:95], v[154:157], v[202:205], v[92:95]
	v_mfma_f32_16x16x32_bf16 v[88:91], v[162:165], v[202:205], v[88:91]
	v_mfma_f32_16x16x32_bf16 v[76:79], v[154:157], v[210:213], v[76:79]
	v_mfma_f32_16x16x32_bf16 v[72:75], v[162:165], v[210:213], v[72:75]
	s_setprio 0
	s_setprio 1
	v_mfma_f32_16x16x32_bf16 v[116:119], v[166:169], v[182:185], v[116:119]
	v_mfma_f32_16x16x32_bf16 v[112:115], v[174:177], v[182:185], v[112:115]
	v_mfma_f32_16x16x32_bf16 v[100:103], v[166:169], v[190:193], v[100:103]
	v_mfma_f32_16x16x32_bf16 v[96:99], v[174:177], v[190:193], v[96:99]
	v_mfma_f32_16x16x32_bf16 v[84:87], v[166:169], v[198:201], v[84:87]
	v_mfma_f32_16x16x32_bf16 v[80:83], v[174:177], v[198:201], v[80:83]
	v_mfma_f32_16x16x32_bf16 v[68:71], v[166:169], v[206:209], v[68:71]
	v_mfma_f32_16x16x32_bf16 v[64:67], v[174:177], v[206:209], v[64:67]
	v_mfma_f32_16x16x32_bf16 v[116:119], v[170:173], v[186:189], v[116:119]
	v_mfma_f32_16x16x32_bf16 v[112:115], v[178:181], v[186:189], v[112:115]
	v_mfma_f32_16x16x32_bf16 v[100:103], v[170:173], v[194:197], v[100:103]
	v_mfma_f32_16x16x32_bf16 v[96:99], v[178:181], v[194:197], v[96:99]
	v_mfma_f32_16x16x32_bf16 v[84:87], v[170:173], v[202:205], v[84:87]
	v_mfma_f32_16x16x32_bf16 v[80:83], v[178:181], v[202:205], v[80:83]
	v_mfma_f32_16x16x32_bf16 v[68:71], v[170:173], v[210:213], v[68:71]
	v_mfma_f32_16x16x32_bf16 v[64:67], v[178:181], v[210:213], v[64:67]
	s_setprio 0
	s_barrier
	s_add_i32 s62, s50, s3
	v_lshl_add_u64 v[214:215], s[38:39], 0, v[130:131]
	s_mov_b32 m0, s62
	ds_read_b128 v[182:185], v149 offset:16384
	ds_read_b128 v[186:189], v149 offset:17408
	ds_read_b128 v[190:193], v149 offset:18432
	ds_read_b128 v[194:197], v149 offset:19456
	ds_read_b128 v[198:201], v149 offset:20480
	ds_read_b128 v[202:205], v149 offset:21504
	ds_read_b128 v[206:209], v149 offset:22528
	ds_read_b128 v[210:213], v149 offset:23552
	global_load_lds_dwordx4 v[214:215], off
	s_add_i32 m0, s62, 0x2000
	s_add_u32 s62, s38, 0x40000
	v_lshl_add_u64 v[216:217], s[38:39], 0, v[134:135]
	s_addc_u32 s63, s39, 0
	s_add_i32 s64, s51, s3
	global_load_lds_dwordx4 v[216:217], off
	v_lshl_add_u64 v[218:219], s[62:63], 0, v[130:131]
	s_mov_b32 m0, s64
	v_lshl_add_u64 v[222:223], s[40:41], 0, v[132:133]
	global_load_lds_dwordx4 v[218:219], off
	v_lshl_add_u64 v[218:219], s[62:63], 0, v[134:135]
	s_add_i32 m0, s64, 0x2000
	s_nop 0
	global_load_lds_dwordx4 v[218:219], off
	v_lshl_add_u64 v[218:219], s[40:41], 0, v[128:129]
	s_mov_b32 m0, s35
	s_nop 0
	global_load_lds_dwordx4 v[218:219], off
	s_mov_b32 m0, s42
	s_nop 0
	global_load_lds_dwordx4 v[222:223], off
	s_waitcnt vmcnt(9)
	s_waitcnt lgkmcnt(0)
	s_barrier
	s_setprio 1
	s_waitcnt lgkmcnt(0)
	v_mfma_f32_16x16x32_bf16 v[60:63], v[150:153], v[182:185], v[60:63]
	v_mfma_f32_16x16x32_bf16 v[56:59], v[158:161], v[182:185], v[56:59]
	v_mfma_f32_16x16x32_bf16 v[44:47], v[150:153], v[190:193], v[44:47]
	v_mfma_f32_16x16x32_bf16 v[40:43], v[158:161], v[190:193], v[40:43]
	v_mfma_f32_16x16x32_bf16 v[28:31], v[150:153], v[198:201], v[28:31]
	v_mfma_f32_16x16x32_bf16 v[24:27], v[158:161], v[198:201], v[24:27]
	v_mfma_f32_16x16x32_bf16 v[12:15], v[150:153], v[206:209], v[12:15]
	v_mfma_f32_16x16x32_bf16 v[8:11], v[158:161], v[206:209], v[8:11]
	v_mfma_f32_16x16x32_bf16 v[60:63], v[154:157], v[186:189], v[60:63]
	v_mfma_f32_16x16x32_bf16 v[56:59], v[162:165], v[186:189], v[56:59]
	v_mfma_f32_16x16x32_bf16 v[44:47], v[154:157], v[194:197], v[44:47]
	v_mfma_f32_16x16x32_bf16 v[40:43], v[162:165], v[194:197], v[40:43]
	v_mfma_f32_16x16x32_bf16 v[28:31], v[154:157], v[202:205], v[28:31]
	v_mfma_f32_16x16x32_bf16 v[24:27], v[162:165], v[202:205], v[24:27]
	v_mfma_f32_16x16x32_bf16 v[12:15], v[154:157], v[210:213], v[12:15]
	v_mfma_f32_16x16x32_bf16 v[8:11], v[162:165], v[210:213], v[8:11]
	s_setprio 0
	s_setprio 1
	v_mfma_f32_16x16x32_bf16 v[52:55], v[166:169], v[182:185], v[52:55]
	v_mfma_f32_16x16x32_bf16 v[48:51], v[174:177], v[182:185], v[48:51]
	v_mfma_f32_16x16x32_bf16 v[36:39], v[166:169], v[190:193], v[36:39]
	v_mfma_f32_16x16x32_bf16 v[32:35], v[174:177], v[190:193], v[32:35]
	v_mfma_f32_16x16x32_bf16 v[20:23], v[166:169], v[198:201], v[20:23]
	v_mfma_f32_16x16x32_bf16 v[16:19], v[174:177], v[198:201], v[16:19]
	v_mfma_f32_16x16x32_bf16 v[4:7], v[166:169], v[206:209], v[4:7]
	v_mfma_f32_16x16x32_bf16 v[0:3], v[174:177], v[206:209], v[0:3]
	v_mfma_f32_16x16x32_bf16 v[52:55], v[170:173], v[186:189], v[52:55]
	v_mfma_f32_16x16x32_bf16 v[48:51], v[178:181], v[186:189], v[48:51]
	v_mfma_f32_16x16x32_bf16 v[36:39], v[170:173], v[194:197], v[36:39]
	v_mfma_f32_16x16x32_bf16 v[32:35], v[178:181], v[194:197], v[32:35]
	v_mfma_f32_16x16x32_bf16 v[20:23], v[170:173], v[202:205], v[20:23]
	v_mfma_f32_16x16x32_bf16 v[16:19], v[178:181], v[202:205], v[16:19]
	v_mfma_f32_16x16x32_bf16 v[4:7], v[170:173], v[210:213], v[4:7]
	v_mfma_f32_16x16x32_bf16 v[0:3], v[178:181], v[210:213], v[0:3]
	s_setprio 0
	s_barrier
	s_add_i32 s62, 0, 0x18000
	s_add_i32 s63, 0, 0x1c000
	v_add_u32_e32 v162, s62, v145
	v_add_u32_e32 v178, s63, v145
	ds_read_b128 v[150:153], v162
	ds_read_b128 v[154:157], v162 offset:1024
	ds_read_b128 v[158:161], v162 offset:2048
	ds_read_b128 v[162:165], v162 offset:3072
	ds_read_b128 v[166:169], v178
	ds_read_b128 v[170:173], v178 offset:1024
	ds_read_b128 v[174:177], v178 offset:2048
	ds_read_b128 v[178:181], v178 offset:3072
	s_add_u32 s40, s40, 0x40000
	s_addc_u32 s41, s41, 0
	s_mov_b32 m0, s43
	v_lshl_add_u64 v[224:225], s[40:41], 0, v[128:129]
	ds_read_b128 v[182:185], v149 offset:32768
	ds_read_b128 v[186:189], v149 offset:33792
	ds_read_b128 v[190:193], v149 offset:34816
	ds_read_b128 v[194:197], v149 offset:35840
	ds_read_b128 v[198:201], v149 offset:36864
	ds_read_b128 v[202:205], v149 offset:37888
	ds_read_b128 v[206:209], v149 offset:38912
	ds_read_b128 v[210:213], v149 offset:39936
	global_load_lds_dwordx4 v[224:225], off
	v_lshl_add_u64 v[224:225], s[40:41], 0, v[132:133]
	s_mov_b32 m0, s44
	s_nop 0
	global_load_lds_dwordx4 v[224:225], off
	s_waitcnt vmcnt(8)
	s_waitcnt lgkmcnt(0)
	s_barrier
	s_setprio 1
	s_waitcnt lgkmcnt(0)
	v_mfma_f32_16x16x32_bf16 v[124:127], v[150:153], v[182:185], v[124:127]
	v_mfma_f32_16x16x32_bf16 v[120:123], v[158:161], v[182:185], v[120:123]
	v_mfma_f32_16x16x32_bf16 v[108:111], v[150:153], v[190:193], v[108:111]
	v_mfma_f32_16x16x32_bf16 v[104:107], v[158:161], v[190:193], v[104:107]
	v_mfma_f32_16x16x32_bf16 v[92:95], v[150:153], v[198:201], v[92:95]
	v_mfma_f32_16x16x32_bf16 v[88:91], v[158:161], v[198:201], v[88:91]
	v_mfma_f32_16x16x32_bf16 v[76:79], v[150:153], v[206:209], v[76:79]
	v_mfma_f32_16x16x32_bf16 v[72:75], v[158:161], v[206:209], v[72:75]
	v_mfma_f32_16x16x32_bf16 v[124:127], v[154:157], v[186:189], v[124:127]
	v_mfma_f32_16x16x32_bf16 v[120:123], v[162:165], v[186:189], v[120:123]
	v_mfma_f32_16x16x32_bf16 v[108:111], v[154:157], v[194:197], v[108:111]
	v_mfma_f32_16x16x32_bf16 v[104:107], v[162:165], v[194:197], v[104:107]
	v_mfma_f32_16x16x32_bf16 v[92:95], v[154:157], v[202:205], v[92:95]
	v_mfma_f32_16x16x32_bf16 v[88:91], v[162:165], v[202:205], v[88:91]
	v_mfma_f32_16x16x32_bf16 v[76:79], v[154:157], v[210:213], v[76:79]
	v_mfma_f32_16x16x32_bf16 v[72:75], v[162:165], v[210:213], v[72:75]
	s_setprio 0
	s_setprio 1
	v_mfma_f32_16x16x32_bf16 v[116:119], v[166:169], v[182:185], v[116:119]
	v_mfma_f32_16x16x32_bf16 v[112:115], v[174:177], v[182:185], v[112:115]
	v_mfma_f32_16x16x32_bf16 v[100:103], v[166:169], v[190:193], v[100:103]
	v_mfma_f32_16x16x32_bf16 v[96:99], v[174:177], v[190:193], v[96:99]
	v_mfma_f32_16x16x32_bf16 v[84:87], v[166:169], v[198:201], v[84:87]
	v_mfma_f32_16x16x32_bf16 v[80:83], v[174:177], v[198:201], v[80:83]
	v_mfma_f32_16x16x32_bf16 v[68:71], v[166:169], v[206:209], v[68:71]
	v_mfma_f32_16x16x32_bf16 v[64:67], v[174:177], v[206:209], v[64:67]
	v_mfma_f32_16x16x32_bf16 v[116:119], v[170:173], v[186:189], v[116:119]
	v_mfma_f32_16x16x32_bf16 v[112:115], v[178:181], v[186:189], v[112:115]
	v_mfma_f32_16x16x32_bf16 v[100:103], v[170:173], v[194:197], v[100:103]
	v_mfma_f32_16x16x32_bf16 v[96:99], v[178:181], v[194:197], v[96:99]
	v_mfma_f32_16x16x32_bf16 v[84:87], v[170:173], v[202:205], v[84:87]
	v_mfma_f32_16x16x32_bf16 v[80:83], v[178:181], v[202:205], v[80:83]
	v_mfma_f32_16x16x32_bf16 v[68:71], v[170:173], v[210:213], v[68:71]
	v_mfma_f32_16x16x32_bf16 v[64:67], v[178:181], v[210:213], v[64:67]
	s_setprio 0
	s_barrier
	s_add_i32 s40, s62, s3
	v_lshl_add_u64 v[214:215], v[214:215], 0, s[12:13]
	s_mov_b32 m0, s40
	ds_read_b128 v[182:185], v149 offset:49152
	ds_read_b128 v[186:189], v149 offset:50176
	ds_read_b128 v[190:193], v149 offset:51200
	ds_read_b128 v[194:197], v149 offset:52224
	ds_read_b128 v[198:201], v149 offset:53248
	ds_read_b128 v[202:205], v149 offset:54272
	ds_read_b128 v[206:209], v149 offset:55296
	ds_read_b128 v[210:213], v149 offset:56320
	global_load_lds_dwordx4 v[214:215], off
	s_add_i32 m0, s40, 0x2000
	s_add_u32 s38, s38, 0x40080
	v_lshl_add_u64 v[214:215], v[216:217], 0, s[12:13]
	s_addc_u32 s39, s39, 0
	s_add_i32 s40, s63, s3
	global_load_lds_dwordx4 v[214:215], off
	v_lshl_add_u64 v[214:215], s[38:39], 0, v[130:131]
	s_mov_b32 m0, s40
	s_nop 0
	global_load_lds_dwordx4 v[214:215], off
	v_lshl_add_u64 v[214:215], s[38:39], 0, v[134:135]
	s_add_i32 m0, s40, 0x2000
	s_nop 0
	global_load_lds_dwordx4 v[214:215], off
	v_lshl_add_u64 v[214:215], v[218:219], 0, s[12:13]
	s_mov_b32 m0, s47
	s_nop 0
	global_load_lds_dwordx4 v[214:215], off
	v_lshl_add_u64 v[214:215], v[222:223], 0, s[12:13]
	s_mov_b32 m0, s48
	s_nop 0
	global_load_lds_dwordx4 v[214:215], off
	s_waitcnt vmcnt(8)
	s_waitcnt lgkmcnt(0)
	s_barrier
	s_setprio 1
	s_waitcnt lgkmcnt(0)
	v_mfma_f32_16x16x32_bf16 v[60:63], v[150:153], v[182:185], v[60:63]
	v_mfma_f32_16x16x32_bf16 v[56:59], v[158:161], v[182:185], v[56:59]
	v_mfma_f32_16x16x32_bf16 v[44:47], v[150:153], v[190:193], v[44:47]
	v_mfma_f32_16x16x32_bf16 v[40:43], v[158:161], v[190:193], v[40:43]
	v_mfma_f32_16x16x32_bf16 v[28:31], v[150:153], v[198:201], v[28:31]
	v_mfma_f32_16x16x32_bf16 v[24:27], v[158:161], v[198:201], v[24:27]
	v_mfma_f32_16x16x32_bf16 v[12:15], v[150:153], v[206:209], v[12:15]
	v_mfma_f32_16x16x32_bf16 v[8:11], v[158:161], v[206:209], v[8:11]
	v_mfma_f32_16x16x32_bf16 v[60:63], v[154:157], v[186:189], v[60:63]
	v_mfma_f32_16x16x32_bf16 v[56:59], v[162:165], v[186:189], v[56:59]
	v_mfma_f32_16x16x32_bf16 v[44:47], v[154:157], v[194:197], v[44:47]
	v_mfma_f32_16x16x32_bf16 v[40:43], v[162:165], v[194:197], v[40:43]
	v_mfma_f32_16x16x32_bf16 v[28:31], v[154:157], v[202:205], v[28:31]
	v_mfma_f32_16x16x32_bf16 v[24:27], v[162:165], v[202:205], v[24:27]
	v_mfma_f32_16x16x32_bf16 v[12:15], v[154:157], v[210:213], v[12:15]
	v_mfma_f32_16x16x32_bf16 v[8:11], v[162:165], v[210:213], v[8:11]
	s_setprio 0
	s_setprio 1
	v_mfma_f32_16x16x32_bf16 v[52:55], v[166:169], v[182:185], v[52:55]
	v_mfma_f32_16x16x32_bf16 v[48:51], v[174:177], v[182:185], v[48:51]
	v_mfma_f32_16x16x32_bf16 v[36:39], v[166:169], v[190:193], v[36:39]
	v_mfma_f32_16x16x32_bf16 v[32:35], v[174:177], v[190:193], v[32:35]
	v_mfma_f32_16x16x32_bf16 v[20:23], v[166:169], v[198:201], v[20:23]
	v_mfma_f32_16x16x32_bf16 v[16:19], v[174:177], v[198:201], v[16:19]
	v_mfma_f32_16x16x32_bf16 v[4:7], v[166:169], v[206:209], v[4:7]
	v_mfma_f32_16x16x32_bf16 v[0:3], v[174:177], v[206:209], v[0:3]
	v_mfma_f32_16x16x32_bf16 v[52:55], v[170:173], v[186:189], v[52:55]
	v_mfma_f32_16x16x32_bf16 v[48:51], v[178:181], v[186:189], v[48:51]
	v_mfma_f32_16x16x32_bf16 v[36:39], v[170:173], v[194:197], v[36:39]
	v_mfma_f32_16x16x32_bf16 v[32:35], v[178:181], v[194:197], v[32:35]
	v_mfma_f32_16x16x32_bf16 v[20:23], v[170:173], v[202:205], v[20:23]
	v_mfma_f32_16x16x32_bf16 v[16:19], v[178:181], v[202:205], v[16:19]
	v_mfma_f32_16x16x32_bf16 v[4:7], v[170:173], v[210:213], v[4:7]
	v_mfma_f32_16x16x32_bf16 v[0:3], v[178:181], v[210:213], v[0:3]
	s_setprio 0
	s_barrier
	s_add_i32 s61, s61, 2
	s_add_u32 s36, s36, 0x100
	s_addc_u32 s37, s37, 0
	s_add_u32 s59, s59, 0x100
	s_addc_u32 s60, s60, 0
	s_cmp_eq_u32 s100, 0
	s_cbranch_scc1 .Ldhs8_idle1
	global_store_dwordx4 v255, v[230:233], s[18:19]
.Ldhs8_done1:
	ds_read_b128 v[150:153], v147
	ds_read_b128 v[154:157], v147 offset:1024
	ds_read_b128 v[158:161], v147 offset:2048
	ds_read_b128 v[162:165], v147 offset:3072
	ds_read_b128 v[166:169], v148
	ds_read_b128 v[170:173], v148 offset:1024
	ds_read_b128 v[174:177], v148 offset:2048
	ds_read_b128 v[178:181], v148 offset:3072
	s_add_u32 s38, s36, 0xfffc0080
	s_addc_u32 s39, s37, -1
	s_cmp_eq_u32 s61, 12
	s_cselect_b32 s41, s27, s39
	s_cselect_b32 s40, s57, s38
	s_cselect_b32 s39, s25, s60
	s_cselect_b32 s38, s58, s59
	v_lshl_add_u64 v[214:215], s[36:37], 0, v[136:137]
	s_add_i32 m0, s35, 0xc000
	ds_read_b128 v[182:185], v149
	ds_read_b128 v[186:189], v149 offset:1024
	ds_read_b128 v[190:193], v149 offset:2048
	ds_read_b128 v[194:197], v149 offset:3072
	ds_read_b128 v[198:201], v149 offset:4096
	ds_read_b128 v[202:205], v149 offset:5120
	ds_read_b128 v[206:209], v149 offset:6144
	ds_read_b128 v[210:213], v149 offset:7168
	global_load_lds_dwordx4 v[214:215], off
	v_lshl_add_u64 v[214:215], s[36:37], 0, v[138:139]
	s_add_i32 m0, s35, 0xe000
	s_nop 0
	global_load_lds_dwordx4 v[214:215], off
	s_waitcnt vmcnt(9)
	s_waitcnt lgkmcnt(0)
	s_barrier
	s_setprio 1
	s_waitcnt lgkmcnt(0)
	v_mfma_f32_16x16x32_bf16 v[124:127], v[150:153], v[182:185], v[124:127]
	v_mfma_f32_16x16x32_bf16 v[120:123], v[158:161], v[182:185], v[120:123]
	v_mfma_f32_16x16x32_bf16 v[108:111], v[150:153], v[190:193], v[108:111]
	v_mfma_f32_16x16x32_bf16 v[104:107], v[158:161], v[190:193], v[104:107]
	v_mfma_f32_16x16x32_bf16 v[92:95], v[150:153], v[198:201], v[92:95]
	v_mfma_f32_16x16x32_bf16 v[88:91], v[158:161], v[198:201], v[88:91]
	v_mfma_f32_16x16x32_bf16 v[76:79], v[150:153], v[206:209], v[76:79]
	v_mfma_f32_16x16x32_bf16 v[72:75], v[158:161], v[206:209], v[72:75]
	v_mfma_f32_16x16x32_bf16 v[124:127], v[154:157], v[186:189], v[124:127]
	v_mfma_f32_16x16x32_bf16 v[120:123], v[162:165], v[186:189], v[120:123]
	v_mfma_f32_16x16x32_bf16 v[108:111], v[154:157], v[194:197], v[108:111]
	v_mfma_f32_16x16x32_bf16 v[104:107], v[162:165], v[194:197], v[104:107]
	v_mfma_f32_16x16x32_bf16 v[92:95], v[154:157], v[202:205], v[92:95]
	v_mfma_f32_16x16x32_bf16 v[88:91], v[162:165], v[202:205], v[88:91]
	v_mfma_f32_16x16x32_bf16 v[76:79], v[154:157], v[210:213], v[76:79]
	v_mfma_f32_16x16x32_bf16 v[72:75], v[162:165], v[210:213], v[72:75]
	s_setprio 0
	s_setprio 1
	v_mfma_f32_16x16x32_bf16 v[116:119], v[166:169], v[182:185], v[116:119]
	v_mfma_f32_16x16x32_bf16 v[112:115], v[174:177], v[182:185], v[112:115]
	v_mfma_f32_16x16x32_bf16 v[100:103], v[166:169], v[190:193], v[100:103]
	v_mfma_f32_16x16x32_bf16 v[96:99], v[174:177], v[190:193], v[96:99]
	v_mfma_f32_16x16x32_bf16 v[84:87], v[166:169], v[198:201], v[84:87]
	v_mfma_f32_16x16x32_bf16 v[80:83], v[174:177], v[198:201], v[80:83]
	v_mfma_f32_16x16x32_bf16 v[68:71], v[166:169], v[206:209], v[68:71]
	v_mfma_f32_16x16x32_bf16 v[64:67], v[174:177], v[206:209], v[64:67]
	v_mfma_f32_16x16x32_bf16 v[116:119], v[170:173], v[186:189], v[116:119]
	v_mfma_f32_16x16x32_bf16 v[112:115], v[178:181], v[186:189], v[112:115]
	v_mfma_f32_16x16x32_bf16 v[100:103], v[170:173], v[194:197], v[100:103]
	v_mfma_f32_16x16x32_bf16 v[96:99], v[178:181], v[194:197], v[96:99]
	v_mfma_f32_16x16x32_bf16 v[84:87], v[170:173], v[202:205], v[84:87]
	v_mfma_f32_16x16x32_bf16 v[80:83], v[178:181], v[202:205], v[80:83]
	v_mfma_f32_16x16x32_bf16 v[68:71], v[170:173], v[210:213], v[68:71]
	v_mfma_f32_16x16x32_bf16 v[64:67], v[178:181], v[210:213], v[64:67]
	s_setprio 0
	s_barrier
	s_add_i32 s62, s50, s3
	v_lshl_add_u64 v[214:215], s[38:39], 0, v[130:131]
	s_mov_b32 m0, s62
	ds_read_b128 v[182:185], v149 offset:16384
	ds_read_b128 v[186:189], v149 offset:17408
	ds_read_b128 v[190:193], v149 offset:18432
	ds_read_b128 v[194:197], v149 offset:19456
	ds_read_b128 v[198:201], v149 offset:20480
	ds_read_b128 v[202:205], v149 offset:21504
	ds_read_b128 v[206:209], v149 offset:22528
	ds_read_b128 v[210:213], v149 offset:23552
	global_load_lds_dwordx4 v[214:215], off
	s_add_i32 m0, s62, 0x2000
	s_add_u32 s62, s38, 0x40000
	v_lshl_add_u64 v[216:217], s[38:39], 0, v[134:135]
	s_addc_u32 s63, s39, 0
	s_add_i32 s64, s51, s3
	global_load_lds_dwordx4 v[216:217], off
	v_lshl_add_u64 v[218:219], s[62:63], 0, v[130:131]
	s_mov_b32 m0, s64
	v_lshl_add_u64 v[222:223], s[40:41], 0, v[132:133]
	global_load_lds_dwordx4 v[218:219], off
	v_lshl_add_u64 v[218:219], s[62:63], 0, v[134:135]
	s_add_i32 m0, s64, 0x2000
	s_nop 0
	global_load_lds_dwordx4 v[218:219], off
	v_lshl_add_u64 v[218:219], s[40:41], 0, v[128:129]
	s_mov_b32 m0, s35
	s_nop 0
	global_load_lds_dwordx4 v[218:219], off
	s_mov_b32 m0, s42
	s_nop 0
	global_load_lds_dwordx4 v[222:223], off
	s_waitcnt vmcnt(9)
	s_waitcnt lgkmcnt(0)
	s_barrier
	s_setprio 1
	s_waitcnt lgkmcnt(0)
	v_mfma_f32_16x16x32_bf16 v[60:63], v[150:153], v[182:185], v[60:63]
	v_mfma_f32_16x16x32_bf16 v[56:59], v[158:161], v[182:185], v[56:59]
	v_mfma_f32_16x16x32_bf16 v[44:47], v[150:153], v[190:193], v[44:47]
	v_mfma_f32_16x16x32_bf16 v[40:43], v[158:161], v[190:193], v[40:43]
	v_mfma_f32_16x16x32_bf16 v[28:31], v[150:153], v[198:201], v[28:31]
	v_mfma_f32_16x16x32_bf16 v[24:27], v[158:161], v[198:201], v[24:27]
	v_mfma_f32_16x16x32_bf16 v[12:15], v[150:153], v[206:209], v[12:15]
	v_mfma_f32_16x16x32_bf16 v[8:11], v[158:161], v[206:209], v[8:11]
	v_mfma_f32_16x16x32_bf16 v[60:63], v[154:157], v[186:189], v[60:63]
	v_mfma_f32_16x16x32_bf16 v[56:59], v[162:165], v[186:189], v[56:59]
	v_mfma_f32_16x16x32_bf16 v[44:47], v[154:157], v[194:197], v[44:47]
	v_mfma_f32_16x16x32_bf16 v[40:43], v[162:165], v[194:197], v[40:43]
	v_mfma_f32_16x16x32_bf16 v[28:31], v[154:157], v[202:205], v[28:31]
	v_mfma_f32_16x16x32_bf16 v[24:27], v[162:165], v[202:205], v[24:27]
	v_mfma_f32_16x16x32_bf16 v[12:15], v[154:157], v[210:213], v[12:15]
	v_mfma_f32_16x16x32_bf16 v[8:11], v[162:165], v[210:213], v[8:11]
	s_setprio 0
	s_setprio 1
	v_mfma_f32_16x16x32_bf16 v[52:55], v[166:169], v[182:185], v[52:55]
	v_mfma_f32_16x16x32_bf16 v[48:51], v[174:177], v[182:185], v[48:51]
	v_mfma_f32_16x16x32_bf16 v[36:39], v[166:169], v[190:193], v[36:39]
	v_mfma_f32_16x16x32_bf16 v[32:35], v[174:177], v[190:193], v[32:35]
	v_mfma_f32_16x16x32_bf16 v[20:23], v[166:169], v[198:201], v[20:23]
	v_mfma_f32_16x16x32_bf16 v[16:19], v[174:177], v[198:201], v[16:19]
	v_mfma_f32_16x16x32_bf16 v[4:7], v[166:169], v[206:209], v[4:7]
	v_mfma_f32_16x16x32_bf16 v[0:3], v[174:177], v[206:209], v[0:3]
	v_mfma_f32_16x16x32_bf16 v[52:55], v[170:173], v[186:189], v[52:55]
	v_mfma_f32_16x16x32_bf16 v[48:51], v[178:181], v[186:189], v[48:51]
	v_mfma_f32_16x16x32_bf16 v[36:39], v[170:173], v[194:197], v[36:39]
	v_mfma_f32_16x16x32_bf16 v[32:35], v[178:181], v[194:197], v[32:35]
	v_mfma_f32_16x16x32_bf16 v[20:23], v[170:173], v[202:205], v[20:23]
	v_mfma_f32_16x16x32_bf16 v[16:19], v[178:181], v[202:205], v[16:19]
	v_mfma_f32_16x16x32_bf16 v[4:7], v[170:173], v[210:213], v[4:7]
	v_mfma_f32_16x16x32_bf16 v[0:3], v[178:181], v[210:213], v[0:3]
	s_setprio 0
	s_barrier
	s_add_i32 s62, 0, 0x18000
	s_add_i32 s63, 0, 0x1c000
	v_add_u32_e32 v162, s62, v145
	v_add_u32_e32 v178, s63, v145
	ds_read_b128 v[150:153], v162
	ds_read_b128 v[154:157], v162 offset:1024
	ds_read_b128 v[158:161], v162 offset:2048
	ds_read_b128 v[162:165], v162 offset:3072
	ds_read_b128 v[166:169], v178
	ds_read_b128 v[170:173], v178 offset:1024
	ds_read_b128 v[174:177], v178 offset:2048
	ds_read_b128 v[178:181], v178 offset:3072
	s_add_u32 s40, s40, 0x40000
	s_addc_u32 s41, s41, 0
	s_mov_b32 m0, s43
	v_lshl_add_u64 v[224:225], s[40:41], 0, v[128:129]
	ds_read_b128 v[182:185], v149 offset:32768
	ds_read_b128 v[186:189], v149 offset:33792
	ds_read_b128 v[190:193], v149 offset:34816
	ds_read_b128 v[194:197], v149 offset:35840
	ds_read_b128 v[198:201], v149 offset:36864
	ds_read_b128 v[202:205], v149 offset:37888
	ds_read_b128 v[206:209], v149 offset:38912
	ds_read_b128 v[210:213], v149 offset:39936
	global_load_lds_dwordx4 v[224:225], off
	v_lshl_add_u64 v[224:225], s[40:41], 0, v[132:133]
	s_mov_b32 m0, s44
	s_nop 0
	global_load_lds_dwordx4 v[224:225], off
	s_waitcnt vmcnt(8)
	s_waitcnt lgkmcnt(0)
	s_barrier
	s_setprio 1
	s_waitcnt lgkmcnt(0)
	v_mfma_f32_16x16x32_bf16 v[124:127], v[150:153], v[182:185], v[124:127]
	v_mfma_f32_16x16x32_bf16 v[120:123], v[158:161], v[182:185], v[120:123]
	v_mfma_f32_16x16x32_bf16 v[108:111], v[150:153], v[190:193], v[108:111]
	v_mfma_f32_16x16x32_bf16 v[104:107], v[158:161], v[190:193], v[104:107]
	v_mfma_f32_16x16x32_bf16 v[92:95], v[150:153], v[198:201], v[92:95]
	v_mfma_f32_16x16x32_bf16 v[88:91], v[158:161], v[198:201], v[88:91]
	v_mfma_f32_16x16x32_bf16 v[76:79], v[150:153], v[206:209], v[76:79]
	v_mfma_f32_16x16x32_bf16 v[72:75], v[158:161], v[206:209], v[72:75]
	v_mfma_f32_16x16x32_bf16 v[124:127], v[154:157], v[186:189], v[124:127]
	v_mfma_f32_16x16x32_bf16 v[120:123], v[162:165], v[186:189], v[120:123]
	v_mfma_f32_16x16x32_bf16 v[108:111], v[154:157], v[194:197], v[108:111]
	v_mfma_f32_16x16x32_bf16 v[104:107], v[162:165], v[194:197], v[104:107]
	v_mfma_f32_16x16x32_bf16 v[92:95], v[154:157], v[202:205], v[92:95]
	v_mfma_f32_16x16x32_bf16 v[88:91], v[162:165], v[202:205], v[88:91]
	v_mfma_f32_16x16x32_bf16 v[76:79], v[154:157], v[210:213], v[76:79]
	v_mfma_f32_16x16x32_bf16 v[72:75], v[162:165], v[210:213], v[72:75]
	s_setprio 0
	s_setprio 1
	v_mfma_f32_16x16x32_bf16 v[116:119], v[166:169], v[182:185], v[116:119]
	v_mfma_f32_16x16x32_bf16 v[112:115], v[174:177], v[182:185], v[112:115]
	v_mfma_f32_16x16x32_bf16 v[100:103], v[166:169], v[190:193], v[100:103]
	v_mfma_f32_16x16x32_bf16 v[96:99], v[174:177], v[190:193], v[96:99]
	v_mfma_f32_16x16x32_bf16 v[84:87], v[166:169], v[198:201], v[84:87]
	v_mfma_f32_16x16x32_bf16 v[80:83], v[174:177], v[198:201], v[80:83]
	v_mfma_f32_16x16x32_bf16 v[68:71], v[166:169], v[206:209], v[68:71]
	v_mfma_f32_16x16x32_bf16 v[64:67], v[174:177], v[206:209], v[64:67]
	v_mfma_f32_16x16x32_bf16 v[116:119], v[170:173], v[186:189], v[116:119]
	v_mfma_f32_16x16x32_bf16 v[112:115], v[178:181], v[186:189], v[112:115]
	v_mfma_f32_16x16x32_bf16 v[100:103], v[170:173], v[194:197], v[100:103]
	v_mfma_f32_16x16x32_bf16 v[96:99], v[178:181], v[194:197], v[96:99]
	v_mfma_f32_16x16x32_bf16 v[84:87], v[170:173], v[202:205], v[84:87]
	v_mfma_f32_16x16x32_bf16 v[80:83], v[178:181], v[202:205], v[80:83]
	v_mfma_f32_16x16x32_bf16 v[68:71], v[170:173], v[210:213], v[68:71]
	v_mfma_f32_16x16x32_bf16 v[64:67], v[178:181], v[210:213], v[64:67]
	s_setprio 0
	s_barrier
	s_add_i32 s40, s62, s3
	v_lshl_add_u64 v[214:215], v[214:215], 0, s[12:13]
	s_mov_b32 m0, s40
	ds_read_b128 v[182:185], v149 offset:49152
	ds_read_b128 v[186:189], v149 offset:50176
	ds_read_b128 v[190:193], v149 offset:51200
	ds_read_b128 v[194:197], v149 offset:52224
	ds_read_b128 v[198:201], v149 offset:53248
	ds_read_b128 v[202:205], v149 offset:54272
	ds_read_b128 v[206:209], v149 offset:55296
	ds_read_b128 v[210:213], v149 offset:56320
	global_load_lds_dwordx4 v[214:215], off
	s_add_i32 m0, s40, 0x2000
	s_add_u32 s38, s38, 0x40080
	v_lshl_add_u64 v[214:215], v[216:217], 0, s[12:13]
	s_addc_u32 s39, s39, 0
	s_add_i32 s40, s63, s3
	global_load_lds_dwordx4 v[214:215], off
	v_lshl_add_u64 v[214:215], s[38:39], 0, v[130:131]
	s_mov_b32 m0, s40
	s_nop 0
	global_load_lds_dwordx4 v[214:215], off
	v_lshl_add_u64 v[214:215], s[38:39], 0, v[134:135]
	s_add_i32 m0, s40, 0x2000
	s_nop 0
	global_load_lds_dwordx4 v[214:215], off
	v_lshl_add_u64 v[214:215], v[218:219], 0, s[12:13]
	s_mov_b32 m0, s47
	s_nop 0
	global_load_lds_dwordx4 v[214:215], off
	v_lshl_add_u64 v[214:215], v[222:223], 0, s[12:13]
	s_mov_b32 m0, s48
	s_nop 0
	global_load_lds_dwordx4 v[214:215], off
	s_waitcnt vmcnt(8)
	s_waitcnt lgkmcnt(0)
	s_barrier
	s_setprio 1
	s_waitcnt lgkmcnt(0)
	v_mfma_f32_16x16x32_bf16 v[60:63], v[150:153], v[182:185], v[60:63]
	v_mfma_f32_16x16x32_bf16 v[56:59], v[158:161], v[182:185], v[56:59]
	v_mfma_f32_16x16x32_bf16 v[44:47], v[150:153], v[190:193], v[44:47]
	v_mfma_f32_16x16x32_bf16 v[40:43], v[158:161], v[190:193], v[40:43]
	v_mfma_f32_16x16x32_bf16 v[28:31], v[150:153], v[198:201], v[28:31]
	v_mfma_f32_16x16x32_bf16 v[24:27], v[158:161], v[198:201], v[24:27]
	v_mfma_f32_16x16x32_bf16 v[12:15], v[150:153], v[206:209], v[12:15]
	v_mfma_f32_16x16x32_bf16 v[8:11], v[158:161], v[206:209], v[8:11]
	v_mfma_f32_16x16x32_bf16 v[60:63], v[154:157], v[186:189], v[60:63]
	v_mfma_f32_16x16x32_bf16 v[56:59], v[162:165], v[186:189], v[56:59]
	v_mfma_f32_16x16x32_bf16 v[44:47], v[154:157], v[194:197], v[44:47]
	v_mfma_f32_16x16x32_bf16 v[40:43], v[162:165], v[194:197], v[40:43]
	v_mfma_f32_16x16x32_bf16 v[28:31], v[154:157], v[202:205], v[28:31]
	v_mfma_f32_16x16x32_bf16 v[24:27], v[162:165], v[202:205], v[24:27]
	v_mfma_f32_16x16x32_bf16 v[12:15], v[154:157], v[210:213], v[12:15]
	v_mfma_f32_16x16x32_bf16 v[8:11], v[162:165], v[210:213], v[8:11]
	s_setprio 0
	s_setprio 1
	v_mfma_f32_16x16x32_bf16 v[52:55], v[166:169], v[182:185], v[52:55]
	v_mfma_f32_16x16x32_bf16 v[48:51], v[174:177], v[182:185], v[48:51]
	v_mfma_f32_16x16x32_bf16 v[36:39], v[166:169], v[190:193], v[36:39]
	v_mfma_f32_16x16x32_bf16 v[32:35], v[174:177], v[190:193], v[32:35]
	v_mfma_f32_16x16x32_bf16 v[20:23], v[166:169], v[198:201], v[20:23]
	v_mfma_f32_16x16x32_bf16 v[16:19], v[174:177], v[198:201], v[16:19]
	v_mfma_f32_16x16x32_bf16 v[4:7], v[166:169], v[206:209], v[4:7]
	v_mfma_f32_16x16x32_bf16 v[0:3], v[174:177], v[206:209], v[0:3]
	v_mfma_f32_16x16x32_bf16 v[52:55], v[170:173], v[186:189], v[52:55]
	v_mfma_f32_16x16x32_bf16 v[48:51], v[178:181], v[186:189], v[48:51]
	v_mfma_f32_16x16x32_bf16 v[36:39], v[170:173], v[194:197], v[36:39]
	v_mfma_f32_16x16x32_bf16 v[32:35], v[178:181], v[194:197], v[32:35]
	v_mfma_f32_16x16x32_bf16 v[20:23], v[170:173], v[202:205], v[20:23]
	v_mfma_f32_16x16x32_bf16 v[16:19], v[178:181], v[202:205], v[16:19]
	v_mfma_f32_16x16x32_bf16 v[4:7], v[170:173], v[210:213], v[4:7]
	v_mfma_f32_16x16x32_bf16 v[0:3], v[178:181], v[210:213], v[0:3]
	s_setprio 0
	s_barrier
	s_add_i32 s61, s61, 2
	s_add_u32 s36, s36, 0x100
	s_addc_u32 s37, s37, 0
	s_add_u32 s59, s59, 0x100
	s_addc_u32 s60, s60, 0
	s_cmp_eq_u32 s100, 0
	s_cbranch_scc1 .Ldhs8_idle2
	global_store_dwordx4 v255, v[234:237], s[16:17] offset:1024
.Ldhs8_done2:
	ds_read_b128 v[150:153], v147
	ds_read_b128 v[154:157], v147 offset:1024
	ds_read_b128 v[158:161], v147 offset:2048
	ds_read_b128 v[162:165], v147 offset:3072
	ds_read_b128 v[166:169], v148
	ds_read_b128 v[170:173], v148 offset:1024
	ds_read_b128 v[174:177], v148 offset:2048
	ds_read_b128 v[178:181], v148 offset:3072
	s_add_u32 s38, s36, 0xfffc0080
	s_addc_u32 s39, s37, -1
	s_cmp_eq_u32 s61, 12
	s_cselect_b32 s41, s27, s39
	s_cselect_b32 s40, s57, s38
	s_cselect_b32 s39, s25, s60
	s_cselect_b32 s38, s58, s59
	v_lshl_add_u64 v[214:215], s[36:37], 0, v[136:137]
	s_add_i32 m0, s35, 0xc000
	ds_read_b128 v[182:185], v149
	ds_read_b128 v[186:189], v149 offset:1024
	ds_read_b128 v[190:193], v149 offset:2048
	ds_read_b128 v[194:197], v149 offset:3072
	ds_read_b128 v[198:201], v149 offset:4096
	ds_read_b128 v[202:205], v149 offset:5120
	ds_read_b128 v[206:209], v149 offset:6144
	ds_read_b128 v[210:213], v149 offset:7168
	global_load_lds_dwordx4 v[214:215], off
	v_lshl_add_u64 v[214:215], s[36:37], 0, v[138:139]
	s_add_i32 m0, s35, 0xe000
	s_nop 0
	global_load_lds_dwordx4 v[214:215], off
	s_waitcnt vmcnt(9)
	s_waitcnt lgkmcnt(0)
	s_barrier
	s_setprio 1
	s_waitcnt lgkmcnt(0)
	v_mfma_f32_16x16x32_bf16 v[124:127], v[150:153], v[182:185], v[124:127]
	v_mfma_f32_16x16x32_bf16 v[120:123], v[158:161], v[182:185], v[120:123]
	v_mfma_f32_16x16x32_bf16 v[108:111], v[150:153], v[190:193], v[108:111]
	v_mfma_f32_16x16x32_bf16 v[104:107], v[158:161], v[190:193], v[104:107]
	v_mfma_f32_16x16x32_bf16 v[92:95], v[150:153], v[198:201], v[92:95]
	v_mfma_f32_16x16x32_bf16 v[88:91], v[158:161], v[198:201], v[88:91]
	v_mfma_f32_16x16x32_bf16 v[76:79], v[150:153], v[206:209], v[76:79]
	v_mfma_f32_16x16x32_bf16 v[72:75], v[158:161], v[206:209], v[72:75]
	v_mfma_f32_16x16x32_bf16 v[124:127], v[154:157], v[186:189], v[124:127]
	v_mfma_f32_16x16x32_bf16 v[120:123], v[162:165], v[186:189], v[120:123]
	v_mfma_f32_16x16x32_bf16 v[108:111], v[154:157], v[194:197], v[108:111]
	v_mfma_f32_16x16x32_bf16 v[104:107], v[162:165], v[194:197], v[104:107]
	v_mfma_f32_16x16x32_bf16 v[92:95], v[154:157], v[202:205], v[92:95]
	v_mfma_f32_16x16x32_bf16 v[88:91], v[162:165], v[202:205], v[88:91]
	v_mfma_f32_16x16x32_bf16 v[76:79], v[154:157], v[210:213], v[76:79]
	v_mfma_f32_16x16x32_bf16 v[72:75], v[162:165], v[210:213], v[72:75]
	s_setprio 0
	s_setprio 1
	v_mfma_f32_16x16x32_bf16 v[116:119], v[166:169], v[182:185], v[116:119]
	v_mfma_f32_16x16x32_bf16 v[112:115], v[174:177], v[182:185], v[112:115]
	v_mfma_f32_16x16x32_bf16 v[100:103], v[166:169], v[190:193], v[100:103]
	v_mfma_f32_16x16x32_bf16 v[96:99], v[174:177], v[190:193], v[96:99]
	v_mfma_f32_16x16x32_bf16 v[84:87], v[166:169], v[198:201], v[84:87]
	v_mfma_f32_16x16x32_bf16 v[80:83], v[174:177], v[198:201], v[80:83]
	v_mfma_f32_16x16x32_bf16 v[68:71], v[166:169], v[206:209], v[68:71]
	v_mfma_f32_16x16x32_bf16 v[64:67], v[174:177], v[206:209], v[64:67]
	v_mfma_f32_16x16x32_bf16 v[116:119], v[170:173], v[186:189], v[116:119]
	v_mfma_f32_16x16x32_bf16 v[112:115], v[178:181], v[186:189], v[112:115]
	v_mfma_f32_16x16x32_bf16 v[100:103], v[170:173], v[194:197], v[100:103]
	v_mfma_f32_16x16x32_bf16 v[96:99], v[178:181], v[194:197], v[96:99]
	v_mfma_f32_16x16x32_bf16 v[84:87], v[170:173], v[202:205], v[84:87]
	v_mfma_f32_16x16x32_bf16 v[80:83], v[178:181], v[202:205], v[80:83]
	v_mfma_f32_16x16x32_bf16 v[68:71], v[170:173], v[210:213], v[68:71]
	v_mfma_f32_16x16x32_bf16 v[64:67], v[178:181], v[210:213], v[64:67]
	s_setprio 0
	s_barrier
	s_add_i32 s62, s50, s3
	v_lshl_add_u64 v[214:215], s[38:39], 0, v[130:131]
	s_mov_b32 m0, s62
	ds_read_b128 v[182:185], v149 offset:16384
	ds_read_b128 v[186:189], v149 offset:17408
	ds_read_b128 v[190:193], v149 offset:18432
	ds_read_b128 v[194:197], v149 offset:19456
	ds_read_b128 v[198:201], v149 offset:20480
	ds_read_b128 v[202:205], v149 offset:21504
	ds_read_b128 v[206:209], v149 offset:22528
	ds_read_b128 v[210:213], v149 offset:23552
	global_load_lds_dwordx4 v[214:215], off
	s_add_i32 m0, s62, 0x2000
	s_add_u32 s62, s38, 0x40000
	v_lshl_add_u64 v[216:217], s[38:39], 0, v[134:135]
	s_addc_u32 s63, s39, 0
	s_add_i32 s64, s51, s3
	global_load_lds_dwordx4 v[216:217], off
	v_lshl_add_u64 v[218:219], s[62:63], 0, v[130:131]
	s_mov_b32 m0, s64
	v_lshl_add_u64 v[222:223], s[40:41], 0, v[132:133]
	global_load_lds_dwordx4 v[218:219], off
	v_lshl_add_u64 v[218:219], s[62:63], 0, v[134:135]
	s_add_i32 m0, s64, 0x2000
	s_nop 0
	global_load_lds_dwordx4 v[218:219], off
	v_lshl_add_u64 v[218:219], s[40:41], 0, v[128:129]
	s_mov_b32 m0, s35
	s_nop 0
	global_load_lds_dwordx4 v[218:219], off
	s_mov_b32 m0, s42
	s_nop 0
	global_load_lds_dwordx4 v[222:223], off
	s_waitcnt vmcnt(9)
	s_waitcnt lgkmcnt(0)
	s_barrier
	s_setprio 1
	s_waitcnt lgkmcnt(0)
	v_mfma_f32_16x16x32_bf16 v[60:63], v[150:153], v[182:185], v[60:63]
	v_mfma_f32_16x16x32_bf16 v[56:59], v[158:161], v[182:185], v[56:59]
	v_mfma_f32_16x16x32_bf16 v[44:47], v[150:153], v[190:193], v[44:47]
	v_mfma_f32_16x16x32_bf16 v[40:43], v[158:161], v[190:193], v[40:43]
	v_mfma_f32_16x16x32_bf16 v[28:31], v[150:153], v[198:201], v[28:31]
	v_mfma_f32_16x16x32_bf16 v[24:27], v[158:161], v[198:201], v[24:27]
	v_mfma_f32_16x16x32_bf16 v[12:15], v[150:153], v[206:209], v[12:15]
	v_mfma_f32_16x16x32_bf16 v[8:11], v[158:161], v[206:209], v[8:11]
	v_mfma_f32_16x16x32_bf16 v[60:63], v[154:157], v[186:189], v[60:63]
	v_mfma_f32_16x16x32_bf16 v[56:59], v[162:165], v[186:189], v[56:59]
	v_mfma_f32_16x16x32_bf16 v[44:47], v[154:157], v[194:197], v[44:47]
	v_mfma_f32_16x16x32_bf16 v[40:43], v[162:165], v[194:197], v[40:43]
	v_mfma_f32_16x16x32_bf16 v[28:31], v[154:157], v[202:205], v[28:31]
	v_mfma_f32_16x16x32_bf16 v[24:27], v[162:165], v[202:205], v[24:27]
	v_mfma_f32_16x16x32_bf16 v[12:15], v[154:157], v[210:213], v[12:15]
	v_mfma_f32_16x16x32_bf16 v[8:11], v[162:165], v[210:213], v[8:11]
	s_setprio 0
	s_setprio 1
	v_mfma_f32_16x16x32_bf16 v[52:55], v[166:169], v[182:185], v[52:55]
	v_mfma_f32_16x16x32_bf16 v[48:51], v[174:177], v[182:185], v[48:51]
	v_mfma_f32_16x16x32_bf16 v[36:39], v[166:169], v[190:193], v[36:39]
	v_mfma_f32_16x16x32_bf16 v[32:35], v[174:177], v[190:193], v[32:35]
	v_mfma_f32_16x16x32_bf16 v[20:23], v[166:169], v[198:201], v[20:23]
	v_mfma_f32_16x16x32_bf16 v[16:19], v[174:177], v[198:201], v[16:19]
	v_mfma_f32_16x16x32_bf16 v[4:7], v[166:169], v[206:209], v[4:7]
	v_mfma_f32_16x16x32_bf16 v[0:3], v[174:177], v[206:209], v[0:3]
	v_mfma_f32_16x16x32_bf16 v[52:55], v[170:173], v[186:189], v[52:55]
	v_mfma_f32_16x16x32_bf16 v[48:51], v[178:181], v[186:189], v[48:51]
	v_mfma_f32_16x16x32_bf16 v[36:39], v[170:173], v[194:197], v[36:39]
	v_mfma_f32_16x16x32_bf16 v[32:35], v[178:181], v[194:197], v[32:35]
	v_mfma_f32_16x16x32_bf16 v[20:23], v[170:173], v[202:205], v[20:23]
	v_mfma_f32_16x16x32_bf16 v[16:19], v[178:181], v[202:205], v[16:19]
	v_mfma_f32_16x16x32_bf16 v[4:7], v[170:173], v[210:213], v[4:7]
	v_mfma_f32_16x16x32_bf16 v[0:3], v[178:181], v[210:213], v[0:3]
	s_setprio 0
	s_barrier
	s_add_i32 s62, 0, 0x18000
	s_add_i32 s63, 0, 0x1c000
	v_add_u32_e32 v162, s62, v145
	v_add_u32_e32 v178, s63, v145
	ds_read_b128 v[150:153], v162
	ds_read_b128 v[154:157], v162 offset:1024
	ds_read_b128 v[158:161], v162 offset:2048
	ds_read_b128 v[162:165], v162 offset:3072
	ds_read_b128 v[166:169], v178
	ds_read_b128 v[170:173], v178 offset:1024
	ds_read_b128 v[174:177], v178 offset:2048
	ds_read_b128 v[178:181], v178 offset:3072
	s_add_u32 s40, s40, 0x40000
	s_addc_u32 s41, s41, 0
	s_mov_b32 m0, s43
	v_lshl_add_u64 v[224:225], s[40:41], 0, v[128:129]
	ds_read_b128 v[182:185], v149 offset:32768
	ds_read_b128 v[186:189], v149 offset:33792
	ds_read_b128 v[190:193], v149 offset:34816
	ds_read_b128 v[194:197], v149 offset:35840
	ds_read_b128 v[198:201], v149 offset:36864
	ds_read_b128 v[202:205], v149 offset:37888
	ds_read_b128 v[206:209], v149 offset:38912
	ds_read_b128 v[210:213], v149 offset:39936
	global_load_lds_dwordx4 v[224:225], off
	v_lshl_add_u64 v[224:225], s[40:41], 0, v[132:133]
	s_mov_b32 m0, s44
	s_nop 0
	global_load_lds_dwordx4 v[224:225], off
	s_waitcnt vmcnt(8)
	s_waitcnt lgkmcnt(0)
	s_barrier
	s_setprio 1
	s_waitcnt lgkmcnt(0)
	v_mfma_f32_16x16x32_bf16 v[124:127], v[150:153], v[182:185], v[124:127]
	v_mfma_f32_16x16x32_bf16 v[120:123], v[158:161], v[182:185], v[120:123]
	v_mfma_f32_16x16x32_bf16 v[108:111], v[150:153], v[190:193], v[108:111]
	v_mfma_f32_16x16x32_bf16 v[104:107], v[158:161], v[190:193], v[104:107]
	v_mfma_f32_16x16x32_bf16 v[92:95], v[150:153], v[198:201], v[92:95]
	v_mfma_f32_16x16x32_bf16 v[88:91], v[158:161], v[198:201], v[88:91]
	v_mfma_f32_16x16x32_bf16 v[76:79], v[150:153], v[206:209], v[76:79]
	v_mfma_f32_16x16x32_bf16 v[72:75], v[158:161], v[206:209], v[72:75]
	v_mfma_f32_16x16x32_bf16 v[124:127], v[154:157], v[186:189], v[124:127]
	v_mfma_f32_16x16x32_bf16 v[120:123], v[162:165], v[186:189], v[120:123]
	v_mfma_f32_16x16x32_bf16 v[108:111], v[154:157], v[194:197], v[108:111]
	v_mfma_f32_16x16x32_bf16 v[104:107], v[162:165], v[194:197], v[104:107]
	v_mfma_f32_16x16x32_bf16 v[92:95], v[154:157], v[202:205], v[92:95]
	v_mfma_f32_16x16x32_bf16 v[88:91], v[162:165], v[202:205], v[88:91]
	v_mfma_f32_16x16x32_bf16 v[76:79], v[154:157], v[210:213], v[76:79]
	v_mfma_f32_16x16x32_bf16 v[72:75], v[162:165], v[210:213], v[72:75]
	s_setprio 0
	s_setprio 1
	v_mfma_f32_16x16x32_bf16 v[116:119], v[166:169], v[182:185], v[116:119]
	v_mfma_f32_16x16x32_bf16 v[112:115], v[174:177], v[182:185], v[112:115]
	v_mfma_f32_16x16x32_bf16 v[100:103], v[166:169], v[190:193], v[100:103]
	v_mfma_f32_16x16x32_bf16 v[96:99], v[174:177], v[190:193], v[96:99]
	v_mfma_f32_16x16x32_bf16 v[84:87], v[166:169], v[198:201], v[84:87]
	v_mfma_f32_16x16x32_bf16 v[80:83], v[174:177], v[198:201], v[80:83]
	v_mfma_f32_16x16x32_bf16 v[68:71], v[166:169], v[206:209], v[68:71]
	v_mfma_f32_16x16x32_bf16 v[64:67], v[174:177], v[206:209], v[64:67]
	v_mfma_f32_16x16x32_bf16 v[116:119], v[170:173], v[186:189], v[116:119]
	v_mfma_f32_16x16x32_bf16 v[112:115], v[178:181], v[186:189], v[112:115]
	v_mfma_f32_16x16x32_bf16 v[100:103], v[170:173], v[194:197], v[100:103]
	v_mfma_f32_16x16x32_bf16 v[96:99], v[178:181], v[194:197], v[96:99]
	v_mfma_f32_16x16x32_bf16 v[84:87], v[170:173], v[202:205], v[84:87]
	v_mfma_f32_16x16x32_bf16 v[80:83], v[178:181], v[202:205], v[80:83]
	v_mfma_f32_16x16x32_bf16 v[68:71], v[170:173], v[210:213], v[68:71]
	v_mfma_f32_16x16x32_bf16 v[64:67], v[178:181], v[210:213], v[64:67]
	s_setprio 0
	s_barrier
	s_add_i32 s40, s62, s3
	v_lshl_add_u64 v[214:215], v[214:215], 0, s[12:13]
	s_mov_b32 m0, s40
	ds_read_b128 v[182:185], v149 offset:49152
	ds_read_b128 v[186:189], v149 offset:50176
	ds_read_b128 v[190:193], v149 offset:51200
	ds_read_b128 v[194:197], v149 offset:52224
	ds_read_b128 v[198:201], v149 offset:53248
	ds_read_b128 v[202:205], v149 offset:54272
	ds_read_b128 v[206:209], v149 offset:55296
	ds_read_b128 v[210:213], v149 offset:56320
	global_load_lds_dwordx4 v[214:215], off
	s_add_i32 m0, s40, 0x2000
	s_add_u32 s38, s38, 0x40080
	v_lshl_add_u64 v[214:215], v[216:217], 0, s[12:13]
	s_addc_u32 s39, s39, 0
	s_add_i32 s40, s63, s3
	global_load_lds_dwordx4 v[214:215], off
	v_lshl_add_u64 v[214:215], s[38:39], 0, v[130:131]
	s_mov_b32 m0, s40
	s_nop 0
	global_load_lds_dwordx4 v[214:215], off
	v_lshl_add_u64 v[214:215], s[38:39], 0, v[134:135]
	s_add_i32 m0, s40, 0x2000
	s_nop 0
	global_load_lds_dwordx4 v[214:215], off
	v_lshl_add_u64 v[214:215], v[218:219], 0, s[12:13]
	s_mov_b32 m0, s47
	s_nop 0
	global_load_lds_dwordx4 v[214:215], off
	v_lshl_add_u64 v[214:215], v[222:223], 0, s[12:13]
	s_mov_b32 m0, s48
	s_nop 0
	global_load_lds_dwordx4 v[214:215], off
	s_waitcnt vmcnt(8)
	s_waitcnt lgkmcnt(0)
	s_barrier
	s_setprio 1
	s_waitcnt lgkmcnt(0)
	v_mfma_f32_16x16x32_bf16 v[60:63], v[150:153], v[182:185], v[60:63]
	v_mfma_f32_16x16x32_bf16 v[56:59], v[158:161], v[182:185], v[56:59]
	v_mfma_f32_16x16x32_bf16 v[44:47], v[150:153], v[190:193], v[44:47]
	v_mfma_f32_16x16x32_bf16 v[40:43], v[158:161], v[190:193], v[40:43]
	v_mfma_f32_16x16x32_bf16 v[28:31], v[150:153], v[198:201], v[28:31]
	v_mfma_f32_16x16x32_bf16 v[24:27], v[158:161], v[198:201], v[24:27]
	v_mfma_f32_16x16x32_bf16 v[12:15], v[150:153], v[206:209], v[12:15]
	v_mfma_f32_16x16x32_bf16 v[8:11], v[158:161], v[206:209], v[8:11]
	v_mfma_f32_16x16x32_bf16 v[60:63], v[154:157], v[186:189], v[60:63]
	v_mfma_f32_16x16x32_bf16 v[56:59], v[162:165], v[186:189], v[56:59]
	v_mfma_f32_16x16x32_bf16 v[44:47], v[154:157], v[194:197], v[44:47]
	v_mfma_f32_16x16x32_bf16 v[40:43], v[162:165], v[194:197], v[40:43]
	v_mfma_f32_16x16x32_bf16 v[28:31], v[154:157], v[202:205], v[28:31]
	v_mfma_f32_16x16x32_bf16 v[24:27], v[162:165], v[202:205], v[24:27]
	v_mfma_f32_16x16x32_bf16 v[12:15], v[154:157], v[210:213], v[12:15]
	v_mfma_f32_16x16x32_bf16 v[8:11], v[162:165], v[210:213], v[8:11]
	s_setprio 0
	s_setprio 1
	v_mfma_f32_16x16x32_bf16 v[52:55], v[166:169], v[182:185], v[52:55]
	v_mfma_f32_16x16x32_bf16 v[48:51], v[174:177], v[182:185], v[48:51]
	v_mfma_f32_16x16x32_bf16 v[36:39], v[166:169], v[190:193], v[36:39]
	v_mfma_f32_16x16x32_bf16 v[32:35], v[174:177], v[190:193], v[32:35]
	v_mfma_f32_16x16x32_bf16 v[20:23], v[166:169], v[198:201], v[20:23]
	v_mfma_f32_16x16x32_bf16 v[16:19], v[174:177], v[198:201], v[16:19]
	v_mfma_f32_16x16x32_bf16 v[4:7], v[166:169], v[206:209], v[4:7]
	v_mfma_f32_16x16x32_bf16 v[0:3], v[174:177], v[206:209], v[0:3]
	v_mfma_f32_16x16x32_bf16 v[52:55], v[170:173], v[186:189], v[52:55]
	v_mfma_f32_16x16x32_bf16 v[48:51], v[178:181], v[186:189], v[48:51]
	v_mfma_f32_16x16x32_bf16 v[36:39], v[170:173], v[194:197], v[36:39]
	v_mfma_f32_16x16x32_bf16 v[32:35], v[178:181], v[194:197], v[32:35]
	v_mfma_f32_16x16x32_bf16 v[20:23], v[170:173], v[202:205], v[20:23]
	v_mfma_f32_16x16x32_bf16 v[16:19], v[178:181], v[202:205], v[16:19]
	v_mfma_f32_16x16x32_bf16 v[4:7], v[170:173], v[210:213], v[4:7]
	v_mfma_f32_16x16x32_bf16 v[0:3], v[178:181], v[210:213], v[0:3]
	s_setprio 0
	s_barrier
	s_add_i32 s61, s61, 2
	s_add_u32 s36, s36, 0x100
	s_addc_u32 s37, s37, 0
	s_add_u32 s59, s59, 0x100
	s_addc_u32 s60, s60, 0
	s_cmp_eq_u32 s100, 0
	s_cbranch_scc1 .Ldhs8_idle3
	global_store_dwordx4 v255, v[238:241], s[18:19] offset:1024
.Ldhs8_done3:
	ds_read_b128 v[150:153], v147
	ds_read_b128 v[154:157], v147 offset:1024
	ds_read_b128 v[158:161], v147 offset:2048
	ds_read_b128 v[162:165], v147 offset:3072
	ds_read_b128 v[166:169], v148
	ds_read_b128 v[170:173], v148 offset:1024
	ds_read_b128 v[174:177], v148 offset:2048
	ds_read_b128 v[178:181], v148 offset:3072
	s_add_u32 s38, s36, 0xfffc0080
	s_addc_u32 s39, s37, -1
	s_cmp_eq_u32 s61, 12
	s_cselect_b32 s41, s27, s39
	s_cselect_b32 s40, s57, s38
	s_cselect_b32 s39, s25, s60
	s_cselect_b32 s38, s58, s59
	v_lshl_add_u64 v[214:215], s[36:37], 0, v[136:137]
	s_add_i32 m0, s35, 0xc000
	ds_read_b128 v[182:185], v149
	ds_read_b128 v[186:189], v149 offset:1024
	ds_read_b128 v[190:193], v149 offset:2048
	ds_read_b128 v[194:197], v149 offset:3072
	ds_read_b128 v[198:201], v149 offset:4096
	ds_read_b128 v[202:205], v149 offset:5120
	ds_read_b128 v[206:209], v149 offset:6144
	ds_read_b128 v[210:213], v149 offset:7168
	global_load_lds_dwordx4 v[214:215], off
	v_lshl_add_u64 v[214:215], s[36:37], 0, v[138:139]
	s_add_i32 m0, s35, 0xe000
	s_nop 0
	global_load_lds_dwordx4 v[214:215], off
	s_waitcnt vmcnt(9)
	s_waitcnt lgkmcnt(0)
	s_barrier
	s_setprio 1
	s_waitcnt lgkmcnt(0)
	v_mfma_f32_16x16x32_bf16 v[124:127], v[150:153], v[182:185], v[124:127]
	v_mfma_f32_16x16x32_bf16 v[120:123], v[158:161], v[182:185], v[120:123]
	v_mfma_f32_16x16x32_bf16 v[108:111], v[150:153], v[190:193], v[108:111]
	v_mfma_f32_16x16x32_bf16 v[104:107], v[158:161], v[190:193], v[104:107]
	v_mfma_f32_16x16x32_bf16 v[92:95], v[150:153], v[198:201], v[92:95]
	v_mfma_f32_16x16x32_bf16 v[88:91], v[158:161], v[198:201], v[88:91]
	v_mfma_f32_16x16x32_bf16 v[76:79], v[150:153], v[206:209], v[76:79]
	v_mfma_f32_16x16x32_bf16 v[72:75], v[158:161], v[206:209], v[72:75]
	v_mfma_f32_16x16x32_bf16 v[124:127], v[154:157], v[186:189], v[124:127]
	v_mfma_f32_16x16x32_bf16 v[120:123], v[162:165], v[186:189], v[120:123]
	v_mfma_f32_16x16x32_bf16 v[108:111], v[154:157], v[194:197], v[108:111]
	v_mfma_f32_16x16x32_bf16 v[104:107], v[162:165], v[194:197], v[104:107]
	v_mfma_f32_16x16x32_bf16 v[92:95], v[154:157], v[202:205], v[92:95]
	v_mfma_f32_16x16x32_bf16 v[88:91], v[162:165], v[202:205], v[88:91]
	v_mfma_f32_16x16x32_bf16 v[76:79], v[154:157], v[210:213], v[76:79]
	v_mfma_f32_16x16x32_bf16 v[72:75], v[162:165], v[210:213], v[72:75]
	s_setprio 0
	s_setprio 1
	v_mfma_f32_16x16x32_bf16 v[116:119], v[166:169], v[182:185], v[116:119]
	v_mfma_f32_16x16x32_bf16 v[112:115], v[174:177], v[182:185], v[112:115]
	v_mfma_f32_16x16x32_bf16 v[100:103], v[166:169], v[190:193], v[100:103]
	v_mfma_f32_16x16x32_bf16 v[96:99], v[174:177], v[190:193], v[96:99]
	v_mfma_f32_16x16x32_bf16 v[84:87], v[166:169], v[198:201], v[84:87]
	v_mfma_f32_16x16x32_bf16 v[80:83], v[174:177], v[198:201], v[80:83]
	v_mfma_f32_16x16x32_bf16 v[68:71], v[166:169], v[206:209], v[68:71]
	v_mfma_f32_16x16x32_bf16 v[64:67], v[174:177], v[206:209], v[64:67]
	v_mfma_f32_16x16x32_bf16 v[116:119], v[170:173], v[186:189], v[116:119]
	v_mfma_f32_16x16x32_bf16 v[112:115], v[178:181], v[186:189], v[112:115]
	v_mfma_f32_16x16x32_bf16 v[100:103], v[170:173], v[194:197], v[100:103]
	v_mfma_f32_16x16x32_bf16 v[96:99], v[178:181], v[194:197], v[96:99]
	v_mfma_f32_16x16x32_bf16 v[84:87], v[170:173], v[202:205], v[84:87]
	v_mfma_f32_16x16x32_bf16 v[80:83], v[178:181], v[202:205], v[80:83]
	v_mfma_f32_16x16x32_bf16 v[68:71], v[170:173], v[210:213], v[68:71]
	v_mfma_f32_16x16x32_bf16 v[64:67], v[178:181], v[210:213], v[64:67]
	s_setprio 0
	s_barrier
	s_add_i32 s62, s50, s3
	v_lshl_add_u64 v[214:215], s[38:39], 0, v[130:131]
	s_mov_b32 m0, s62
	ds_read_b128 v[182:185], v149 offset:16384
	ds_read_b128 v[186:189], v149 offset:17408
	ds_read_b128 v[190:193], v149 offset:18432
	ds_read_b128 v[194:197], v149 offset:19456
	ds_read_b128 v[198:201], v149 offset:20480
	ds_read_b128 v[202:205], v149 offset:21504
	ds_read_b128 v[206:209], v149 offset:22528
	ds_read_b128 v[210:213], v149 offset:23552
	global_load_lds_dwordx4 v[214:215], off
	s_add_i32 m0, s62, 0x2000
	s_add_u32 s62, s38, 0x40000
	v_lshl_add_u64 v[216:217], s[38:39], 0, v[134:135]
	s_addc_u32 s63, s39, 0
	s_add_i32 s64, s51, s3
	global_load_lds_dwordx4 v[216:217], off
	v_lshl_add_u64 v[218:219], s[62:63], 0, v[130:131]
	s_mov_b32 m0, s64
	v_lshl_add_u64 v[222:223], s[40:41], 0, v[132:133]
	global_load_lds_dwordx4 v[218:219], off
	v_lshl_add_u64 v[218:219], s[62:63], 0, v[134:135]
	s_add_i32 m0, s64, 0x2000
	s_nop 0
	global_load_lds_dwordx4 v[218:219], off
	v_lshl_add_u64 v[218:219], s[40:41], 0, v[128:129]
	s_mov_b32 m0, s35
	s_nop 0
	global_load_lds_dwordx4 v[218:219], off
	s_mov_b32 m0, s42
	s_nop 0
	global_load_lds_dwordx4 v[222:223], off
	s_waitcnt vmcnt(9)
	s_waitcnt lgkmcnt(0)
	s_barrier
	s_setprio 1
	s_waitcnt lgkmcnt(0)
	v_mfma_f32_16x16x32_bf16 v[60:63], v[150:153], v[182:185], v[60:63]
	v_mfma_f32_16x16x32_bf16 v[56:59], v[158:161], v[182:185], v[56:59]
	v_mfma_f32_16x16x32_bf16 v[44:47], v[150:153], v[190:193], v[44:47]
	v_mfma_f32_16x16x32_bf16 v[40:43], v[158:161], v[190:193], v[40:43]
	v_mfma_f32_16x16x32_bf16 v[28:31], v[150:153], v[198:201], v[28:31]
	v_mfma_f32_16x16x32_bf16 v[24:27], v[158:161], v[198:201], v[24:27]
	v_mfma_f32_16x16x32_bf16 v[12:15], v[150:153], v[206:209], v[12:15]
	v_mfma_f32_16x16x32_bf16 v[8:11], v[158:161], v[206:209], v[8:11]
	v_mfma_f32_16x16x32_bf16 v[60:63], v[154:157], v[186:189], v[60:63]
	v_mfma_f32_16x16x32_bf16 v[56:59], v[162:165], v[186:189], v[56:59]
	v_mfma_f32_16x16x32_bf16 v[44:47], v[154:157], v[194:197], v[44:47]
	v_mfma_f32_16x16x32_bf16 v[40:43], v[162:165], v[194:197], v[40:43]
	v_mfma_f32_16x16x32_bf16 v[28:31], v[154:157], v[202:205], v[28:31]
	v_mfma_f32_16x16x32_bf16 v[24:27], v[162:165], v[202:205], v[24:27]
	v_mfma_f32_16x16x32_bf16 v[12:15], v[154:157], v[210:213], v[12:15]
	v_mfma_f32_16x16x32_bf16 v[8:11], v[162:165], v[210:213], v[8:11]
	s_setprio 0
	s_setprio 1
	v_mfma_f32_16x16x32_bf16 v[52:55], v[166:169], v[182:185], v[52:55]
	v_mfma_f32_16x16x32_bf16 v[48:51], v[174:177], v[182:185], v[48:51]
	v_mfma_f32_16x16x32_bf16 v[36:39], v[166:169], v[190:193], v[36:39]
	v_mfma_f32_16x16x32_bf16 v[32:35], v[174:177], v[190:193], v[32:35]
	v_mfma_f32_16x16x32_bf16 v[20:23], v[166:169], v[198:201], v[20:23]
	v_mfma_f32_16x16x32_bf16 v[16:19], v[174:177], v[198:201], v[16:19]
	v_mfma_f32_16x16x32_bf16 v[4:7], v[166:169], v[206:209], v[4:7]
	v_mfma_f32_16x16x32_bf16 v[0:3], v[174:177], v[206:209], v[0:3]
	v_mfma_f32_16x16x32_bf16 v[52:55], v[170:173], v[186:189], v[52:55]
	v_mfma_f32_16x16x32_bf16 v[48:51], v[178:181], v[186:189], v[48:51]
	v_mfma_f32_16x16x32_bf16 v[36:39], v[170:173], v[194:197], v[36:39]
	v_mfma_f32_16x16x32_bf16 v[32:35], v[178:181], v[194:197], v[32:35]
	v_mfma_f32_16x16x32_bf16 v[20:23], v[170:173], v[202:205], v[20:23]
	v_mfma_f32_16x16x32_bf16 v[16:19], v[178:181], v[202:205], v[16:19]
	v_mfma_f32_16x16x32_bf16 v[4:7], v[170:173], v[210:213], v[4:7]
	v_mfma_f32_16x16x32_bf16 v[0:3], v[178:181], v[210:213], v[0:3]
	s_setprio 0
	s_barrier
	s_add_i32 s62, 0, 0x18000
	s_add_i32 s63, 0, 0x1c000
	v_add_u32_e32 v162, s62, v145
	v_add_u32_e32 v178, s63, v145
	ds_read_b128 v[150:153], v162
	ds_read_b128 v[154:157], v162 offset:1024
	ds_read_b128 v[158:161], v162 offset:2048
	ds_read_b128 v[162:165], v162 offset:3072
	ds_read_b128 v[166:169], v178
	ds_read_b128 v[170:173], v178 offset:1024
	ds_read_b128 v[174:177], v178 offset:2048
	ds_read_b128 v[178:181], v178 offset:3072
	s_add_u32 s40, s40, 0x40000
	s_addc_u32 s41, s41, 0
	s_mov_b32 m0, s43
	v_lshl_add_u64 v[224:225], s[40:41], 0, v[128:129]
	ds_read_b128 v[182:185], v149 offset:32768
	ds_read_b128 v[186:189], v149 offset:33792
	ds_read_b128 v[190:193], v149 offset:34816
	ds_read_b128 v[194:197], v149 offset:35840
	ds_read_b128 v[198:201], v149 offset:36864
	ds_read_b128 v[202:205], v149 offset:37888
	ds_read_b128 v[206:209], v149 offset:38912
	ds_read_b128 v[210:213], v149 offset:39936
	global_load_lds_dwordx4 v[224:225], off
	v_lshl_add_u64 v[224:225], s[40:41], 0, v[132:133]
	s_mov_b32 m0, s44
	s_nop 0
	global_load_lds_dwordx4 v[224:225], off
	s_waitcnt vmcnt(8)
	s_waitcnt lgkmcnt(0)
	s_barrier
	s_setprio 1
	s_waitcnt lgkmcnt(0)
	v_mfma_f32_16x16x32_bf16 v[124:127], v[150:153], v[182:185], v[124:127]
	v_mfma_f32_16x16x32_bf16 v[120:123], v[158:161], v[182:185], v[120:123]
	v_mfma_f32_16x16x32_bf16 v[108:111], v[150:153], v[190:193], v[108:111]
	v_mfma_f32_16x16x32_bf16 v[104:107], v[158:161], v[190:193], v[104:107]
	v_mfma_f32_16x16x32_bf16 v[92:95], v[150:153], v[198:201], v[92:95]
	v_mfma_f32_16x16x32_bf16 v[88:91], v[158:161], v[198:201], v[88:91]
	v_mfma_f32_16x16x32_bf16 v[76:79], v[150:153], v[206:209], v[76:79]
	v_mfma_f32_16x16x32_bf16 v[72:75], v[158:161], v[206:209], v[72:75]
	v_mfma_f32_16x16x32_bf16 v[124:127], v[154:157], v[186:189], v[124:127]
	v_mfma_f32_16x16x32_bf16 v[120:123], v[162:165], v[186:189], v[120:123]
	v_mfma_f32_16x16x32_bf16 v[108:111], v[154:157], v[194:197], v[108:111]
	v_mfma_f32_16x16x32_bf16 v[104:107], v[162:165], v[194:197], v[104:107]
	v_mfma_f32_16x16x32_bf16 v[92:95], v[154:157], v[202:205], v[92:95]
	v_mfma_f32_16x16x32_bf16 v[88:91], v[162:165], v[202:205], v[88:91]
	v_mfma_f32_16x16x32_bf16 v[76:79], v[154:157], v[210:213], v[76:79]
	v_mfma_f32_16x16x32_bf16 v[72:75], v[162:165], v[210:213], v[72:75]
	s_setprio 0
	s_setprio 1
	v_mfma_f32_16x16x32_bf16 v[116:119], v[166:169], v[182:185], v[116:119]
	v_mfma_f32_16x16x32_bf16 v[112:115], v[174:177], v[182:185], v[112:115]
	v_mfma_f32_16x16x32_bf16 v[100:103], v[166:169], v[190:193], v[100:103]
	v_mfma_f32_16x16x32_bf16 v[96:99], v[174:177], v[190:193], v[96:99]
	v_mfma_f32_16x16x32_bf16 v[84:87], v[166:169], v[198:201], v[84:87]
	v_mfma_f32_16x16x32_bf16 v[80:83], v[174:177], v[198:201], v[80:83]
	v_mfma_f32_16x16x32_bf16 v[68:71], v[166:169], v[206:209], v[68:71]
	v_mfma_f32_16x16x32_bf16 v[64:67], v[174:177], v[206:209], v[64:67]
	v_mfma_f32_16x16x32_bf16 v[116:119], v[170:173], v[186:189], v[116:119]
	v_mfma_f32_16x16x32_bf16 v[112:115], v[178:181], v[186:189], v[112:115]
	v_mfma_f32_16x16x32_bf16 v[100:103], v[170:173], v[194:197], v[100:103]
	v_mfma_f32_16x16x32_bf16 v[96:99], v[178:181], v[194:197], v[96:99]
	v_mfma_f32_16x16x32_bf16 v[84:87], v[170:173], v[202:205], v[84:87]
	v_mfma_f32_16x16x32_bf16 v[80:83], v[178:181], v[202:205], v[80:83]
	v_mfma_f32_16x16x32_bf16 v[68:71], v[170:173], v[210:213], v[68:71]
	v_mfma_f32_16x16x32_bf16 v[64:67], v[178:181], v[210:213], v[64:67]
	s_setprio 0
	s_barrier
	s_add_i32 s40, s62, s3
	v_lshl_add_u64 v[214:215], v[214:215], 0, s[12:13]
	s_mov_b32 m0, s40
	ds_read_b128 v[182:185], v149 offset:49152
	ds_read_b128 v[186:189], v149 offset:50176
	ds_read_b128 v[190:193], v149 offset:51200
	ds_read_b128 v[194:197], v149 offset:52224
	ds_read_b128 v[198:201], v149 offset:53248
	ds_read_b128 v[202:205], v149 offset:54272
	ds_read_b128 v[206:209], v149 offset:55296
	ds_read_b128 v[210:213], v149 offset:56320
	global_load_lds_dwordx4 v[214:215], off
	s_add_i32 m0, s40, 0x2000
	s_add_u32 s38, s38, 0x40080
	v_lshl_add_u64 v[214:215], v[216:217], 0, s[12:13]
	s_addc_u32 s39, s39, 0
	s_add_i32 s40, s63, s3
	global_load_lds_dwordx4 v[214:215], off
	v_lshl_add_u64 v[214:215], s[38:39], 0, v[130:131]
	s_mov_b32 m0, s40
	s_nop 0
	global_load_lds_dwordx4 v[214:215], off
	v_lshl_add_u64 v[214:215], s[38:39], 0, v[134:135]
	s_add_i32 m0, s40, 0x2000
	s_nop 0
	global_load_lds_dwordx4 v[214:215], off
	v_lshl_add_u64 v[214:215], v[218:219], 0, s[12:13]
	s_mov_b32 m0, s47
	s_nop 0
	global_load_lds_dwordx4 v[214:215], off
	v_lshl_add_u64 v[214:215], v[222:223], 0, s[12:13]
	s_mov_b32 m0, s48
	s_nop 0
	global_load_lds_dwordx4 v[214:215], off
	s_waitcnt vmcnt(8)
	s_waitcnt lgkmcnt(0)
	s_barrier
	s_setprio 1
	s_waitcnt lgkmcnt(0)
	v_mfma_f32_16x16x32_bf16 v[60:63], v[150:153], v[182:185], v[60:63]
	v_mfma_f32_16x16x32_bf16 v[56:59], v[158:161], v[182:185], v[56:59]
	v_mfma_f32_16x16x32_bf16 v[44:47], v[150:153], v[190:193], v[44:47]
	v_mfma_f32_16x16x32_bf16 v[40:43], v[158:161], v[190:193], v[40:43]
	v_mfma_f32_16x16x32_bf16 v[28:31], v[150:153], v[198:201], v[28:31]
	v_mfma_f32_16x16x32_bf16 v[24:27], v[158:161], v[198:201], v[24:27]
	v_mfma_f32_16x16x32_bf16 v[12:15], v[150:153], v[206:209], v[12:15]
	v_mfma_f32_16x16x32_bf16 v[8:11], v[158:161], v[206:209], v[8:11]
	v_mfma_f32_16x16x32_bf16 v[60:63], v[154:157], v[186:189], v[60:63]
	v_mfma_f32_16x16x32_bf16 v[56:59], v[162:165], v[186:189], v[56:59]
	v_mfma_f32_16x16x32_bf16 v[44:47], v[154:157], v[194:197], v[44:47]
	v_mfma_f32_16x16x32_bf16 v[40:43], v[162:165], v[194:197], v[40:43]
	v_mfma_f32_16x16x32_bf16 v[28:31], v[154:157], v[202:205], v[28:31]
	v_mfma_f32_16x16x32_bf16 v[24:27], v[162:165], v[202:205], v[24:27]
	v_mfma_f32_16x16x32_bf16 v[12:15], v[154:157], v[210:213], v[12:15]
	v_mfma_f32_16x16x32_bf16 v[8:11], v[162:165], v[210:213], v[8:11]
	s_setprio 0
	s_setprio 1
	v_mfma_f32_16x16x32_bf16 v[52:55], v[166:169], v[182:185], v[52:55]
	v_mfma_f32_16x16x32_bf16 v[48:51], v[174:177], v[182:185], v[48:51]
	v_mfma_f32_16x16x32_bf16 v[36:39], v[166:169], v[190:193], v[36:39]
	v_mfma_f32_16x16x32_bf16 v[32:35], v[174:177], v[190:193], v[32:35]
	v_mfma_f32_16x16x32_bf16 v[20:23], v[166:169], v[198:201], v[20:23]
	v_mfma_f32_16x16x32_bf16 v[16:19], v[174:177], v[198:201], v[16:19]
	v_mfma_f32_16x16x32_bf16 v[4:7], v[166:169], v[206:209], v[4:7]
	v_mfma_f32_16x16x32_bf16 v[0:3], v[174:177], v[206:209], v[0:3]
	v_mfma_f32_16x16x32_bf16 v[52:55], v[170:173], v[186:189], v[52:55]
	v_mfma_f32_16x16x32_bf16 v[48:51], v[178:181], v[186:189], v[48:51]
	v_mfma_f32_16x16x32_bf16 v[36:39], v[170:173], v[194:197], v[36:39]
	v_mfma_f32_16x16x32_bf16 v[32:35], v[178:181], v[194:197], v[32:35]
	v_mfma_f32_16x16x32_bf16 v[20:23], v[170:173], v[202:205], v[20:23]
	v_mfma_f32_16x16x32_bf16 v[16:19], v[178:181], v[202:205], v[16:19]
	v_mfma_f32_16x16x32_bf16 v[4:7], v[170:173], v[210:213], v[4:7]
	v_mfma_f32_16x16x32_bf16 v[0:3], v[178:181], v[210:213], v[0:3]
	s_setprio 0
	s_barrier
	s_add_i32 s61, s61, 2
	s_add_u32 s36, s36, 0x100
	s_addc_u32 s37, s37, 0
	s_add_u32 s59, s59, 0x100
	s_addc_u32 s60, s60, 0
	s_cmp_eq_u32 s100, 0
	s_cbranch_scc1 .Ldhs8_idle4
	global_store_dwordx4 v255, v[242:245], s[16:17] offset:2048
.Ldhs8_done4:
	ds_read_b128 v[150:153], v147
	ds_read_b128 v[154:157], v147 offset:1024
	ds_read_b128 v[158:161], v147 offset:2048
	ds_read_b128 v[162:165], v147 offset:3072
	ds_read_b128 v[166:169], v148
	ds_read_b128 v[170:173], v148 offset:1024
	ds_read_b128 v[174:177], v148 offset:2048
	ds_read_b128 v[178:181], v148 offset:3072
	s_add_u32 s38, s36, 0xfffc0080
	s_addc_u32 s39, s37, -1
	s_cmp_eq_u32 s61, 12
	s_cselect_b32 s41, s27, s39
	s_cselect_b32 s40, s57, s38
	s_cselect_b32 s39, s25, s60
	s_cselect_b32 s38, s58, s59
	v_lshl_add_u64 v[214:215], s[36:37], 0, v[136:137]
	s_add_i32 m0, s35, 0xc000
	ds_read_b128 v[182:185], v149
	ds_read_b128 v[186:189], v149 offset:1024
	ds_read_b128 v[190:193], v149 offset:2048
	ds_read_b128 v[194:197], v149 offset:3072
	ds_read_b128 v[198:201], v149 offset:4096
	ds_read_b128 v[202:205], v149 offset:5120
	ds_read_b128 v[206:209], v149 offset:6144
	ds_read_b128 v[210:213], v149 offset:7168
	global_load_lds_dwordx4 v[214:215], off
	v_lshl_add_u64 v[214:215], s[36:37], 0, v[138:139]
	s_add_i32 m0, s35, 0xe000
	s_nop 0
	global_load_lds_dwordx4 v[214:215], off
	s_waitcnt vmcnt(9)
	s_waitcnt lgkmcnt(0)
	s_barrier
	s_setprio 1
	s_waitcnt lgkmcnt(0)
	v_mfma_f32_16x16x32_bf16 v[124:127], v[150:153], v[182:185], v[124:127]
	v_mfma_f32_16x16x32_bf16 v[120:123], v[158:161], v[182:185], v[120:123]
	v_mfma_f32_16x16x32_bf16 v[108:111], v[150:153], v[190:193], v[108:111]
	v_mfma_f32_16x16x32_bf16 v[104:107], v[158:161], v[190:193], v[104:107]
	v_mfma_f32_16x16x32_bf16 v[92:95], v[150:153], v[198:201], v[92:95]
	v_mfma_f32_16x16x32_bf16 v[88:91], v[158:161], v[198:201], v[88:91]
	v_mfma_f32_16x16x32_bf16 v[76:79], v[150:153], v[206:209], v[76:79]
	v_mfma_f32_16x16x32_bf16 v[72:75], v[158:161], v[206:209], v[72:75]
	v_mfma_f32_16x16x32_bf16 v[124:127], v[154:157], v[186:189], v[124:127]
	v_mfma_f32_16x16x32_bf16 v[120:123], v[162:165], v[186:189], v[120:123]
	v_mfma_f32_16x16x32_bf16 v[108:111], v[154:157], v[194:197], v[108:111]
	v_mfma_f32_16x16x32_bf16 v[104:107], v[162:165], v[194:197], v[104:107]
	v_mfma_f32_16x16x32_bf16 v[92:95], v[154:157], v[202:205], v[92:95]
	v_mfma_f32_16x16x32_bf16 v[88:91], v[162:165], v[202:205], v[88:91]
	v_mfma_f32_16x16x32_bf16 v[76:79], v[154:157], v[210:213], v[76:79]
	v_mfma_f32_16x16x32_bf16 v[72:75], v[162:165], v[210:213], v[72:75]
	s_setprio 0
	s_setprio 1
	v_mfma_f32_16x16x32_bf16 v[116:119], v[166:169], v[182:185], v[116:119]
	v_mfma_f32_16x16x32_bf16 v[112:115], v[174:177], v[182:185], v[112:115]
	v_mfma_f32_16x16x32_bf16 v[100:103], v[166:169], v[190:193], v[100:103]
	v_mfma_f32_16x16x32_bf16 v[96:99], v[174:177], v[190:193], v[96:99]
	v_mfma_f32_16x16x32_bf16 v[84:87], v[166:169], v[198:201], v[84:87]
	v_mfma_f32_16x16x32_bf16 v[80:83], v[174:177], v[198:201], v[80:83]
	v_mfma_f32_16x16x32_bf16 v[68:71], v[166:169], v[206:209], v[68:71]
	v_mfma_f32_16x16x32_bf16 v[64:67], v[174:177], v[206:209], v[64:67]
	v_mfma_f32_16x16x32_bf16 v[116:119], v[170:173], v[186:189], v[116:119]
	v_mfma_f32_16x16x32_bf16 v[112:115], v[178:181], v[186:189], v[112:115]
	v_mfma_f32_16x16x32_bf16 v[100:103], v[170:173], v[194:197], v[100:103]
	v_mfma_f32_16x16x32_bf16 v[96:99], v[178:181], v[194:197], v[96:99]
	v_mfma_f32_16x16x32_bf16 v[84:87], v[170:173], v[202:205], v[84:87]
	v_mfma_f32_16x16x32_bf16 v[80:83], v[178:181], v[202:205], v[80:83]
	v_mfma_f32_16x16x32_bf16 v[68:71], v[170:173], v[210:213], v[68:71]
	v_mfma_f32_16x16x32_bf16 v[64:67], v[178:181], v[210:213], v[64:67]
	s_setprio 0
	s_barrier
	s_add_i32 s62, s50, s3
	v_lshl_add_u64 v[214:215], s[38:39], 0, v[130:131]
	s_mov_b32 m0, s62
	ds_read_b128 v[182:185], v149 offset:16384
	ds_read_b128 v[186:189], v149 offset:17408
	ds_read_b128 v[190:193], v149 offset:18432
	ds_read_b128 v[194:197], v149 offset:19456
	ds_read_b128 v[198:201], v149 offset:20480
	ds_read_b128 v[202:205], v149 offset:21504
	ds_read_b128 v[206:209], v149 offset:22528
	ds_read_b128 v[210:213], v149 offset:23552
	global_load_lds_dwordx4 v[214:215], off
	s_add_i32 m0, s62, 0x2000
	s_add_u32 s62, s38, 0x40000
	v_lshl_add_u64 v[216:217], s[38:39], 0, v[134:135]
	s_addc_u32 s63, s39, 0
	s_add_i32 s64, s51, s3
	global_load_lds_dwordx4 v[216:217], off
	v_lshl_add_u64 v[218:219], s[62:63], 0, v[130:131]
	s_mov_b32 m0, s64
	v_lshl_add_u64 v[222:223], s[40:41], 0, v[132:133]
	global_load_lds_dwordx4 v[218:219], off
	v_lshl_add_u64 v[218:219], s[62:63], 0, v[134:135]
	s_add_i32 m0, s64, 0x2000
	s_nop 0
	global_load_lds_dwordx4 v[218:219], off
	v_lshl_add_u64 v[218:219], s[40:41], 0, v[128:129]
	s_mov_b32 m0, s35
	s_nop 0
	global_load_lds_dwordx4 v[218:219], off
	s_mov_b32 m0, s42
	s_nop 0
	global_load_lds_dwordx4 v[222:223], off
	s_waitcnt vmcnt(9)
	s_waitcnt lgkmcnt(0)
	s_barrier
	s_setprio 1
	s_waitcnt lgkmcnt(0)
	v_mfma_f32_16x16x32_bf16 v[60:63], v[150:153], v[182:185], v[60:63]
	v_mfma_f32_16x16x32_bf16 v[56:59], v[158:161], v[182:185], v[56:59]
	v_mfma_f32_16x16x32_bf16 v[44:47], v[150:153], v[190:193], v[44:47]
	v_mfma_f32_16x16x32_bf16 v[40:43], v[158:161], v[190:193], v[40:43]
	v_mfma_f32_16x16x32_bf16 v[28:31], v[150:153], v[198:201], v[28:31]
	v_mfma_f32_16x16x32_bf16 v[24:27], v[158:161], v[198:201], v[24:27]
	v_mfma_f32_16x16x32_bf16 v[12:15], v[150:153], v[206:209], v[12:15]
	v_mfma_f32_16x16x32_bf16 v[8:11], v[158:161], v[206:209], v[8:11]
	v_mfma_f32_16x16x32_bf16 v[60:63], v[154:157], v[186:189], v[60:63]
	v_mfma_f32_16x16x32_bf16 v[56:59], v[162:165], v[186:189], v[56:59]
	v_mfma_f32_16x16x32_bf16 v[44:47], v[154:157], v[194:197], v[44:47]
	v_mfma_f32_16x16x32_bf16 v[40:43], v[162:165], v[194:197], v[40:43]
	v_mfma_f32_16x16x32_bf16 v[28:31], v[154:157], v[202:205], v[28:31]
	v_mfma_f32_16x16x32_bf16 v[24:27], v[162:165], v[202:205], v[24:27]
	v_mfma_f32_16x16x32_bf16 v[12:15], v[154:157], v[210:213], v[12:15]
	v_mfma_f32_16x16x32_bf16 v[8:11], v[162:165], v[210:213], v[8:11]
	s_setprio 0
	s_setprio 1
	v_mfma_f32_16x16x32_bf16 v[52:55], v[166:169], v[182:185], v[52:55]
	v_mfma_f32_16x16x32_bf16 v[48:51], v[174:177], v[182:185], v[48:51]
	v_mfma_f32_16x16x32_bf16 v[36:39], v[166:169], v[190:193], v[36:39]
	v_mfma_f32_16x16x32_bf16 v[32:35], v[174:177], v[190:193], v[32:35]
	v_mfma_f32_16x16x32_bf16 v[20:23], v[166:169], v[198:201], v[20:23]
	v_mfma_f32_16x16x32_bf16 v[16:19], v[174:177], v[198:201], v[16:19]
	v_mfma_f32_16x16x32_bf16 v[4:7], v[166:169], v[206:209], v[4:7]
	v_mfma_f32_16x16x32_bf16 v[0:3], v[174:177], v[206:209], v[0:3]
	v_mfma_f32_16x16x32_bf16 v[52:55], v[170:173], v[186:189], v[52:55]
	v_mfma_f32_16x16x32_bf16 v[48:51], v[178:181], v[186:189], v[48:51]
	v_mfma_f32_16x16x32_bf16 v[36:39], v[170:173], v[194:197], v[36:39]
	v_mfma_f32_16x16x32_bf16 v[32:35], v[178:181], v[194:197], v[32:35]
	v_mfma_f32_16x16x32_bf16 v[20:23], v[170:173], v[202:205], v[20:23]
	v_mfma_f32_16x16x32_bf16 v[16:19], v[178:181], v[202:205], v[16:19]
	v_mfma_f32_16x16x32_bf16 v[4:7], v[170:173], v[210:213], v[4:7]
	v_mfma_f32_16x16x32_bf16 v[0:3], v[178:181], v[210:213], v[0:3]
	s_setprio 0
	s_barrier
	s_add_i32 s62, 0, 0x18000
	s_add_i32 s63, 0, 0x1c000
	v_add_u32_e32 v162, s62, v145
	v_add_u32_e32 v178, s63, v145
	ds_read_b128 v[150:153], v162
	ds_read_b128 v[154:157], v162 offset:1024
	ds_read_b128 v[158:161], v162 offset:2048
	ds_read_b128 v[162:165], v162 offset:3072
	ds_read_b128 v[166:169], v178
	ds_read_b128 v[170:173], v178 offset:1024
	ds_read_b128 v[174:177], v178 offset:2048
	ds_read_b128 v[178:181], v178 offset:3072
	s_add_u32 s40, s40, 0x40000
	s_addc_u32 s41, s41, 0
	s_mov_b32 m0, s43
	v_lshl_add_u64 v[224:225], s[40:41], 0, v[128:129]
	ds_read_b128 v[182:185], v149 offset:32768
	ds_read_b128 v[186:189], v149 offset:33792
	ds_read_b128 v[190:193], v149 offset:34816
	ds_read_b128 v[194:197], v149 offset:35840
	ds_read_b128 v[198:201], v149 offset:36864
	ds_read_b128 v[202:205], v149 offset:37888
	ds_read_b128 v[206:209], v149 offset:38912
	ds_read_b128 v[210:213], v149 offset:39936
	global_load_lds_dwordx4 v[224:225], off
	v_lshl_add_u64 v[224:225], s[40:41], 0, v[132:133]
	s_mov_b32 m0, s44
	s_nop 0
	global_load_lds_dwordx4 v[224:225], off
	s_waitcnt vmcnt(8)
	s_waitcnt lgkmcnt(0)
	s_barrier
	s_setprio 1
	s_waitcnt lgkmcnt(0)
	v_mfma_f32_16x16x32_bf16 v[124:127], v[150:153], v[182:185], v[124:127]
	v_mfma_f32_16x16x32_bf16 v[120:123], v[158:161], v[182:185], v[120:123]
	v_mfma_f32_16x16x32_bf16 v[108:111], v[150:153], v[190:193], v[108:111]
	v_mfma_f32_16x16x32_bf16 v[104:107], v[158:161], v[190:193], v[104:107]
	v_mfma_f32_16x16x32_bf16 v[92:95], v[150:153], v[198:201], v[92:95]
	v_mfma_f32_16x16x32_bf16 v[88:91], v[158:161], v[198:201], v[88:91]
	v_mfma_f32_16x16x32_bf16 v[76:79], v[150:153], v[206:209], v[76:79]
	v_mfma_f32_16x16x32_bf16 v[72:75], v[158:161], v[206:209], v[72:75]
	v_mfma_f32_16x16x32_bf16 v[124:127], v[154:157], v[186:189], v[124:127]
	v_mfma_f32_16x16x32_bf16 v[120:123], v[162:165], v[186:189], v[120:123]
	v_mfma_f32_16x16x32_bf16 v[108:111], v[154:157], v[194:197], v[108:111]
	v_mfma_f32_16x16x32_bf16 v[104:107], v[162:165], v[194:197], v[104:107]
	v_mfma_f32_16x16x32_bf16 v[92:95], v[154:157], v[202:205], v[92:95]
	v_mfma_f32_16x16x32_bf16 v[88:91], v[162:165], v[202:205], v[88:91]
	v_mfma_f32_16x16x32_bf16 v[76:79], v[154:157], v[210:213], v[76:79]
	v_mfma_f32_16x16x32_bf16 v[72:75], v[162:165], v[210:213], v[72:75]
	s_setprio 0
	s_setprio 1
	v_mfma_f32_16x16x32_bf16 v[116:119], v[166:169], v[182:185], v[116:119]
	v_mfma_f32_16x16x32_bf16 v[112:115], v[174:177], v[182:185], v[112:115]
	v_mfma_f32_16x16x32_bf16 v[100:103], v[166:169], v[190:193], v[100:103]
	v_mfma_f32_16x16x32_bf16 v[96:99], v[174:177], v[190:193], v[96:99]
	v_mfma_f32_16x16x32_bf16 v[84:87], v[166:169], v[198:201], v[84:87]
	v_mfma_f32_16x16x32_bf16 v[80:83], v[174:177], v[198:201], v[80:83]
	v_mfma_f32_16x16x32_bf16 v[68:71], v[166:169], v[206:209], v[68:71]
	v_mfma_f32_16x16x32_bf16 v[64:67], v[174:177], v[206:209], v[64:67]
	v_mfma_f32_16x16x32_bf16 v[116:119], v[170:173], v[186:189], v[116:119]
	v_mfma_f32_16x16x32_bf16 v[112:115], v[178:181], v[186:189], v[112:115]
	v_mfma_f32_16x16x32_bf16 v[100:103], v[170:173], v[194:197], v[100:103]
	v_mfma_f32_16x16x32_bf16 v[96:99], v[178:181], v[194:197], v[96:99]
	v_mfma_f32_16x16x32_bf16 v[84:87], v[170:173], v[202:205], v[84:87]
	v_mfma_f32_16x16x32_bf16 v[80:83], v[178:181], v[202:205], v[80:83]
	v_mfma_f32_16x16x32_bf16 v[68:71], v[170:173], v[210:213], v[68:71]
	v_mfma_f32_16x16x32_bf16 v[64:67], v[178:181], v[210:213], v[64:67]
	s_setprio 0
	s_barrier
	s_add_i32 s40, s62, s3
	v_lshl_add_u64 v[214:215], v[214:215], 0, s[12:13]
	s_mov_b32 m0, s40
	ds_read_b128 v[182:185], v149 offset:49152
	ds_read_b128 v[186:189], v149 offset:50176
	ds_read_b128 v[190:193], v149 offset:51200
	ds_read_b128 v[194:197], v149 offset:52224
	ds_read_b128 v[198:201], v149 offset:53248
	ds_read_b128 v[202:205], v149 offset:54272
	ds_read_b128 v[206:209], v149 offset:55296
	ds_read_b128 v[210:213], v149 offset:56320
	global_load_lds_dwordx4 v[214:215], off
	s_add_i32 m0, s40, 0x2000
	s_add_u32 s38, s38, 0x40080
	v_lshl_add_u64 v[214:215], v[216:217], 0, s[12:13]
	s_addc_u32 s39, s39, 0
	s_add_i32 s40, s63, s3
	global_load_lds_dwordx4 v[214:215], off
	v_lshl_add_u64 v[214:215], s[38:39], 0, v[130:131]
	s_mov_b32 m0, s40
	s_nop 0
	global_load_lds_dwordx4 v[214:215], off
	v_lshl_add_u64 v[214:215], s[38:39], 0, v[134:135]
	s_add_i32 m0, s40, 0x2000
	s_nop 0
	global_load_lds_dwordx4 v[214:215], off
	v_lshl_add_u64 v[214:215], v[218:219], 0, s[12:13]
	s_mov_b32 m0, s47
	s_nop 0
	global_load_lds_dwordx4 v[214:215], off
	v_lshl_add_u64 v[214:215], v[222:223], 0, s[12:13]
	s_mov_b32 m0, s48
	s_nop 0
	global_load_lds_dwordx4 v[214:215], off
	s_waitcnt vmcnt(8)
	s_waitcnt lgkmcnt(0)
	s_barrier
	s_setprio 1
	s_waitcnt lgkmcnt(0)
	v_mfma_f32_16x16x32_bf16 v[60:63], v[150:153], v[182:185], v[60:63]
	v_mfma_f32_16x16x32_bf16 v[56:59], v[158:161], v[182:185], v[56:59]
	v_mfma_f32_16x16x32_bf16 v[44:47], v[150:153], v[190:193], v[44:47]
	v_mfma_f32_16x16x32_bf16 v[40:43], v[158:161], v[190:193], v[40:43]
	v_mfma_f32_16x16x32_bf16 v[28:31], v[150:153], v[198:201], v[28:31]
	v_mfma_f32_16x16x32_bf16 v[24:27], v[158:161], v[198:201], v[24:27]
	v_mfma_f32_16x16x32_bf16 v[12:15], v[150:153], v[206:209], v[12:15]
	v_mfma_f32_16x16x32_bf16 v[8:11], v[158:161], v[206:209], v[8:11]
	v_mfma_f32_16x16x32_bf16 v[60:63], v[154:157], v[186:189], v[60:63]
	v_mfma_f32_16x16x32_bf16 v[56:59], v[162:165], v[186:189], v[56:59]
	v_mfma_f32_16x16x32_bf16 v[44:47], v[154:157], v[194:197], v[44:47]
	v_mfma_f32_16x16x32_bf16 v[40:43], v[162:165], v[194:197], v[40:43]
	v_mfma_f32_16x16x32_bf16 v[28:31], v[154:157], v[202:205], v[28:31]
	v_mfma_f32_16x16x32_bf16 v[24:27], v[162:165], v[202:205], v[24:27]
	v_mfma_f32_16x16x32_bf16 v[12:15], v[154:157], v[210:213], v[12:15]
	v_mfma_f32_16x16x32_bf16 v[8:11], v[162:165], v[210:213], v[8:11]
	s_setprio 0
	s_setprio 1
	v_mfma_f32_16x16x32_bf16 v[52:55], v[166:169], v[182:185], v[52:55]
	v_mfma_f32_16x16x32_bf16 v[48:51], v[174:177], v[182:185], v[48:51]
	v_mfma_f32_16x16x32_bf16 v[36:39], v[166:169], v[190:193], v[36:39]
	v_mfma_f32_16x16x32_bf16 v[32:35], v[174:177], v[190:193], v[32:35]
	v_mfma_f32_16x16x32_bf16 v[20:23], v[166:169], v[198:201], v[20:23]
	v_mfma_f32_16x16x32_bf16 v[16:19], v[174:177], v[198:201], v[16:19]
	v_mfma_f32_16x16x32_bf16 v[4:7], v[166:169], v[206:209], v[4:7]
	v_mfma_f32_16x16x32_bf16 v[0:3], v[174:177], v[206:209], v[0:3]
	v_mfma_f32_16x16x32_bf16 v[52:55], v[170:173], v[186:189], v[52:55]
	v_mfma_f32_16x16x32_bf16 v[48:51], v[178:181], v[186:189], v[48:51]
	v_mfma_f32_16x16x32_bf16 v[36:39], v[170:173], v[194:197], v[36:39]
	v_mfma_f32_16x16x32_bf16 v[32:35], v[178:181], v[194:197], v[32:35]
	v_mfma_f32_16x16x32_bf16 v[20:23], v[170:173], v[202:205], v[20:23]
	v_mfma_f32_16x16x32_bf16 v[16:19], v[178:181], v[202:205], v[16:19]
	v_mfma_f32_16x16x32_bf16 v[4:7], v[170:173], v[210:213], v[4:7]
	v_mfma_f32_16x16x32_bf16 v[0:3], v[178:181], v[210:213], v[0:3]
	s_setprio 0
	s_barrier
	s_add_i32 s61, s61, 2
	s_add_u32 s36, s36, 0x100
	s_addc_u32 s37, s37, 0
	s_add_u32 s59, s59, 0x100
	s_addc_u32 s60, s60, 0
	s_cmp_eq_u32 s100, 0
	s_cbranch_scc1 .Ldhs8_idle5
	global_store_dwordx4 v255, v[246:249], s[18:19] offset:2048
.Ldhs8_done5:
	ds_read_b128 v[150:153], v147
	ds_read_b128 v[154:157], v147 offset:1024
	ds_read_b128 v[158:161], v147 offset:2048
	ds_read_b128 v[162:165], v147 offset:3072
	ds_read_b128 v[166:169], v148
	ds_read_b128 v[170:173], v148 offset:1024
	ds_read_b128 v[174:177], v148 offset:2048
	ds_read_b128 v[178:181], v148 offset:3072
	s_add_u32 s38, s36, 0xfffc0080
	s_addc_u32 s39, s37, -1
	s_cmp_eq_u32 s61, 12
	s_cselect_b32 s41, s27, s39
	s_cselect_b32 s40, s57, s38
	s_cselect_b32 s39, s25, s60
	s_cselect_b32 s38, s58, s59
	v_lshl_add_u64 v[214:215], s[36:37], 0, v[136:137]
	s_add_i32 m0, s35, 0xc000
	ds_read_b128 v[182:185], v149
	ds_read_b128 v[186:189], v149 offset:1024
	ds_read_b128 v[190:193], v149 offset:2048
	ds_read_b128 v[194:197], v149 offset:3072
	ds_read_b128 v[198:201], v149 offset:4096
	ds_read_b128 v[202:205], v149 offset:5120
	ds_read_b128 v[206:209], v149 offset:6144
	ds_read_b128 v[210:213], v149 offset:7168
	global_load_lds_dwordx4 v[214:215], off
	v_lshl_add_u64 v[214:215], s[36:37], 0, v[138:139]
	s_add_i32 m0, s35, 0xe000
	s_nop 0
	global_load_lds_dwordx4 v[214:215], off
	s_waitcnt vmcnt(9)
	s_waitcnt lgkmcnt(0)
	s_barrier
	s_setprio 1
	s_waitcnt lgkmcnt(0)
	v_mfma_f32_16x16x32_bf16 v[124:127], v[150:153], v[182:185], v[124:127]
	v_mfma_f32_16x16x32_bf16 v[120:123], v[158:161], v[182:185], v[120:123]
	v_mfma_f32_16x16x32_bf16 v[108:111], v[150:153], v[190:193], v[108:111]
	v_mfma_f32_16x16x32_bf16 v[104:107], v[158:161], v[190:193], v[104:107]
	v_mfma_f32_16x16x32_bf16 v[92:95], v[150:153], v[198:201], v[92:95]
	v_mfma_f32_16x16x32_bf16 v[88:91], v[158:161], v[198:201], v[88:91]
	v_mfma_f32_16x16x32_bf16 v[76:79], v[150:153], v[206:209], v[76:79]
	v_mfma_f32_16x16x32_bf16 v[72:75], v[158:161], v[206:209], v[72:75]
	v_mfma_f32_16x16x32_bf16 v[124:127], v[154:157], v[186:189], v[124:127]
	v_mfma_f32_16x16x32_bf16 v[120:123], v[162:165], v[186:189], v[120:123]
	v_mfma_f32_16x16x32_bf16 v[108:111], v[154:157], v[194:197], v[108:111]
	v_mfma_f32_16x16x32_bf16 v[104:107], v[162:165], v[194:197], v[104:107]
	v_mfma_f32_16x16x32_bf16 v[92:95], v[154:157], v[202:205], v[92:95]
	v_mfma_f32_16x16x32_bf16 v[88:91], v[162:165], v[202:205], v[88:91]
	v_mfma_f32_16x16x32_bf16 v[76:79], v[154:157], v[210:213], v[76:79]
	v_mfma_f32_16x16x32_bf16 v[72:75], v[162:165], v[210:213], v[72:75]
	s_setprio 0
	s_setprio 1
	v_mfma_f32_16x16x32_bf16 v[116:119], v[166:169], v[182:185], v[116:119]
	v_mfma_f32_16x16x32_bf16 v[112:115], v[174:177], v[182:185], v[112:115]
	v_mfma_f32_16x16x32_bf16 v[100:103], v[166:169], v[190:193], v[100:103]
	v_mfma_f32_16x16x32_bf16 v[96:99], v[174:177], v[190:193], v[96:99]
	v_mfma_f32_16x16x32_bf16 v[84:87], v[166:169], v[198:201], v[84:87]
	v_mfma_f32_16x16x32_bf16 v[80:83], v[174:177], v[198:201], v[80:83]
	v_mfma_f32_16x16x32_bf16 v[68:71], v[166:169], v[206:209], v[68:71]
	v_mfma_f32_16x16x32_bf16 v[64:67], v[174:177], v[206:209], v[64:67]
	v_mfma_f32_16x16x32_bf16 v[116:119], v[170:173], v[186:189], v[116:119]
	v_mfma_f32_16x16x32_bf16 v[112:115], v[178:181], v[186:189], v[112:115]
	v_mfma_f32_16x16x32_bf16 v[100:103], v[170:173], v[194:197], v[100:103]
	v_mfma_f32_16x16x32_bf16 v[96:99], v[178:181], v[194:197], v[96:99]
	v_mfma_f32_16x16x32_bf16 v[84:87], v[170:173], v[202:205], v[84:87]
	v_mfma_f32_16x16x32_bf16 v[80:83], v[178:181], v[202:205], v[80:83]
	v_mfma_f32_16x16x32_bf16 v[68:71], v[170:173], v[210:213], v[68:71]
	v_mfma_f32_16x16x32_bf16 v[64:67], v[178:181], v[210:213], v[64:67]
	s_setprio 0
	s_barrier
	s_add_i32 s62, s50, s3
	v_lshl_add_u64 v[214:215], s[38:39], 0, v[130:131]
	s_mov_b32 m0, s62
	ds_read_b128 v[182:185], v149 offset:16384
	ds_read_b128 v[186:189], v149 offset:17408
	ds_read_b128 v[190:193], v149 offset:18432
	ds_read_b128 v[194:197], v149 offset:19456
	ds_read_b128 v[198:201], v149 offset:20480
	ds_read_b128 v[202:205], v149 offset:21504
	ds_read_b128 v[206:209], v149 offset:22528
	ds_read_b128 v[210:213], v149 offset:23552
	global_load_lds_dwordx4 v[214:215], off
	s_add_i32 m0, s62, 0x2000
	s_add_u32 s62, s38, 0x40000
	v_lshl_add_u64 v[216:217], s[38:39], 0, v[134:135]
	s_addc_u32 s63, s39, 0
	s_add_i32 s64, s51, s3
	global_load_lds_dwordx4 v[216:217], off
	v_lshl_add_u64 v[218:219], s[62:63], 0, v[130:131]
	s_mov_b32 m0, s64
	v_lshl_add_u64 v[222:223], s[40:41], 0, v[132:133]
	global_load_lds_dwordx4 v[218:219], off
	v_lshl_add_u64 v[218:219], s[62:63], 0, v[134:135]
	s_add_i32 m0, s64, 0x2000
	s_nop 0
	global_load_lds_dwordx4 v[218:219], off
	v_lshl_add_u64 v[218:219], s[40:41], 0, v[128:129]
	s_mov_b32 m0, s35
	s_nop 0
	global_load_lds_dwordx4 v[218:219], off
	s_mov_b32 m0, s42
	s_nop 0
	global_load_lds_dwordx4 v[222:223], off
	s_waitcnt vmcnt(9)
	s_waitcnt lgkmcnt(0)
	s_barrier
	s_setprio 1
	s_waitcnt lgkmcnt(0)
	v_mfma_f32_16x16x32_bf16 v[60:63], v[150:153], v[182:185], v[60:63]
	v_mfma_f32_16x16x32_bf16 v[56:59], v[158:161], v[182:185], v[56:59]
	v_mfma_f32_16x16x32_bf16 v[44:47], v[150:153], v[190:193], v[44:47]
	v_mfma_f32_16x16x32_bf16 v[40:43], v[158:161], v[190:193], v[40:43]
	v_mfma_f32_16x16x32_bf16 v[28:31], v[150:153], v[198:201], v[28:31]
	v_mfma_f32_16x16x32_bf16 v[24:27], v[158:161], v[198:201], v[24:27]
	v_mfma_f32_16x16x32_bf16 v[12:15], v[150:153], v[206:209], v[12:15]
	v_mfma_f32_16x16x32_bf16 v[8:11], v[158:161], v[206:209], v[8:11]
	v_mfma_f32_16x16x32_bf16 v[60:63], v[154:157], v[186:189], v[60:63]
	v_mfma_f32_16x16x32_bf16 v[56:59], v[162:165], v[186:189], v[56:59]
	v_mfma_f32_16x16x32_bf16 v[44:47], v[154:157], v[194:197], v[44:47]
	v_mfma_f32_16x16x32_bf16 v[40:43], v[162:165], v[194:197], v[40:43]
	v_mfma_f32_16x16x32_bf16 v[28:31], v[154:157], v[202:205], v[28:31]
	v_mfma_f32_16x16x32_bf16 v[24:27], v[162:165], v[202:205], v[24:27]
	v_mfma_f32_16x16x32_bf16 v[12:15], v[154:157], v[210:213], v[12:15]
	v_mfma_f32_16x16x32_bf16 v[8:11], v[162:165], v[210:213], v[8:11]
	s_setprio 0
	s_setprio 1
	v_mfma_f32_16x16x32_bf16 v[52:55], v[166:169], v[182:185], v[52:55]
	v_mfma_f32_16x16x32_bf16 v[48:51], v[174:177], v[182:185], v[48:51]
	v_mfma_f32_16x16x32_bf16 v[36:39], v[166:169], v[190:193], v[36:39]
	v_mfma_f32_16x16x32_bf16 v[32:35], v[174:177], v[190:193], v[32:35]
	v_mfma_f32_16x16x32_bf16 v[20:23], v[166:169], v[198:201], v[20:23]
	v_mfma_f32_16x16x32_bf16 v[16:19], v[174:177], v[198:201], v[16:19]
	v_mfma_f32_16x16x32_bf16 v[4:7], v[166:169], v[206:209], v[4:7]
	v_mfma_f32_16x16x32_bf16 v[0:3], v[174:177], v[206:209], v[0:3]
	v_mfma_f32_16x16x32_bf16 v[52:55], v[170:173], v[186:189], v[52:55]
	v_mfma_f32_16x16x32_bf16 v[48:51], v[178:181], v[186:189], v[48:51]
	v_mfma_f32_16x16x32_bf16 v[36:39], v[170:173], v[194:197], v[36:39]
	v_mfma_f32_16x16x32_bf16 v[32:35], v[178:181], v[194:197], v[32:35]
	v_mfma_f32_16x16x32_bf16 v[20:23], v[170:173], v[202:205], v[20:23]
	v_mfma_f32_16x16x32_bf16 v[16:19], v[178:181], v[202:205], v[16:19]
	v_mfma_f32_16x16x32_bf16 v[4:7], v[170:173], v[210:213], v[4:7]
	v_mfma_f32_16x16x32_bf16 v[0:3], v[178:181], v[210:213], v[0:3]
	s_setprio 0
	s_barrier
	s_add_i32 s62, 0, 0x18000
	s_add_i32 s63, 0, 0x1c000
	v_add_u32_e32 v162, s62, v145
	v_add_u32_e32 v178, s63, v145
	ds_read_b128 v[150:153], v162
	ds_read_b128 v[154:157], v162 offset:1024
	ds_read_b128 v[158:161], v162 offset:2048
	ds_read_b128 v[162:165], v162 offset:3072
	ds_read_b128 v[166:169], v178
	ds_read_b128 v[170:173], v178 offset:1024
	ds_read_b128 v[174:177], v178 offset:2048
	ds_read_b128 v[178:181], v178 offset:3072
	s_add_u32 s40, s40, 0x40000
	s_addc_u32 s41, s41, 0
	s_mov_b32 m0, s43
	v_lshl_add_u64 v[224:225], s[40:41], 0, v[128:129]
	ds_read_b128 v[182:185], v149 offset:32768
	ds_read_b128 v[186:189], v149 offset:33792
	ds_read_b128 v[190:193], v149 offset:34816
	ds_read_b128 v[194:197], v149 offset:35840
	ds_read_b128 v[198:201], v149 offset:36864
	ds_read_b128 v[202:205], v149 offset:37888
	ds_read_b128 v[206:209], v149 offset:38912
	ds_read_b128 v[210:213], v149 offset:39936
	global_load_lds_dwordx4 v[224:225], off
	v_lshl_add_u64 v[224:225], s[40:41], 0, v[132:133]
	s_mov_b32 m0, s44
	s_nop 0
	global_load_lds_dwordx4 v[224:225], off
	s_waitcnt vmcnt(8)
	s_waitcnt lgkmcnt(0)
	s_barrier
	s_setprio 1
	s_waitcnt lgkmcnt(0)
	v_mfma_f32_16x16x32_bf16 v[124:127], v[150:153], v[182:185], v[124:127]
	v_mfma_f32_16x16x32_bf16 v[120:123], v[158:161], v[182:185], v[120:123]
	v_mfma_f32_16x16x32_bf16 v[108:111], v[150:153], v[190:193], v[108:111]
	v_mfma_f32_16x16x32_bf16 v[104:107], v[158:161], v[190:193], v[104:107]
	v_mfma_f32_16x16x32_bf16 v[92:95], v[150:153], v[198:201], v[92:95]
	v_mfma_f32_16x16x32_bf16 v[88:91], v[158:161], v[198:201], v[88:91]
	v_mfma_f32_16x16x32_bf16 v[76:79], v[150:153], v[206:209], v[76:79]
	v_mfma_f32_16x16x32_bf16 v[72:75], v[158:161], v[206:209], v[72:75]
	v_mfma_f32_16x16x32_bf16 v[124:127], v[154:157], v[186:189], v[124:127]
	v_mfma_f32_16x16x32_bf16 v[120:123], v[162:165], v[186:189], v[120:123]
	v_mfma_f32_16x16x32_bf16 v[108:111], v[154:157], v[194:197], v[108:111]
	v_mfma_f32_16x16x32_bf16 v[104:107], v[162:165], v[194:197], v[104:107]
	v_mfma_f32_16x16x32_bf16 v[92:95], v[154:157], v[202:205], v[92:95]
	v_mfma_f32_16x16x32_bf16 v[88:91], v[162:165], v[202:205], v[88:91]
	v_mfma_f32_16x16x32_bf16 v[76:79], v[154:157], v[210:213], v[76:79]
	v_mfma_f32_16x16x32_bf16 v[72:75], v[162:165], v[210:213], v[72:75]
	s_setprio 0
	s_setprio 1
	v_mfma_f32_16x16x32_bf16 v[116:119], v[166:169], v[182:185], v[116:119]
	v_mfma_f32_16x16x32_bf16 v[112:115], v[174:177], v[182:185], v[112:115]
	v_mfma_f32_16x16x32_bf16 v[100:103], v[166:169], v[190:193], v[100:103]
	v_mfma_f32_16x16x32_bf16 v[96:99], v[174:177], v[190:193], v[96:99]
	v_mfma_f32_16x16x32_bf16 v[84:87], v[166:169], v[198:201], v[84:87]
	v_mfma_f32_16x16x32_bf16 v[80:83], v[174:177], v[198:201], v[80:83]
	v_mfma_f32_16x16x32_bf16 v[68:71], v[166:169], v[206:209], v[68:71]
	v_mfma_f32_16x16x32_bf16 v[64:67], v[174:177], v[206:209], v[64:67]
	v_mfma_f32_16x16x32_bf16 v[116:119], v[170:173], v[186:189], v[116:119]
	v_mfma_f32_16x16x32_bf16 v[112:115], v[178:181], v[186:189], v[112:115]
	v_mfma_f32_16x16x32_bf16 v[100:103], v[170:173], v[194:197], v[100:103]
	v_mfma_f32_16x16x32_bf16 v[96:99], v[178:181], v[194:197], v[96:99]
	v_mfma_f32_16x16x32_bf16 v[84:87], v[170:173], v[202:205], v[84:87]
	v_mfma_f32_16x16x32_bf16 v[80:83], v[178:181], v[202:205], v[80:83]
	v_mfma_f32_16x16x32_bf16 v[68:71], v[170:173], v[210:213], v[68:71]
	v_mfma_f32_16x16x32_bf16 v[64:67], v[178:181], v[210:213], v[64:67]
	s_setprio 0
	s_barrier
	s_add_i32 s40, s62, s3
	v_lshl_add_u64 v[214:215], v[214:215], 0, s[12:13]
	s_mov_b32 m0, s40
	ds_read_b128 v[182:185], v149 offset:49152
	ds_read_b128 v[186:189], v149 offset:50176
	ds_read_b128 v[190:193], v149 offset:51200
	ds_read_b128 v[194:197], v149 offset:52224
	ds_read_b128 v[198:201], v149 offset:53248
	ds_read_b128 v[202:205], v149 offset:54272
	ds_read_b128 v[206:209], v149 offset:55296
	ds_read_b128 v[210:213], v149 offset:56320
	global_load_lds_dwordx4 v[214:215], off
	s_add_i32 m0, s40, 0x2000
	s_add_u32 s38, s38, 0x40080
	v_lshl_add_u64 v[214:215], v[216:217], 0, s[12:13]
	s_addc_u32 s39, s39, 0
	s_add_i32 s40, s63, s3
	global_load_lds_dwordx4 v[214:215], off
	v_lshl_add_u64 v[214:215], s[38:39], 0, v[130:131]
	s_mov_b32 m0, s40
	s_nop 0
	global_load_lds_dwordx4 v[214:215], off
	v_lshl_add_u64 v[214:215], s[38:39], 0, v[134:135]
	s_add_i32 m0, s40, 0x2000
	s_nop 0
	global_load_lds_dwordx4 v[214:215], off
	v_lshl_add_u64 v[214:215], v[218:219], 0, s[12:13]
	s_mov_b32 m0, s47
	s_nop 0
	global_load_lds_dwordx4 v[214:215], off
	v_lshl_add_u64 v[214:215], v[222:223], 0, s[12:13]
	s_mov_b32 m0, s48
	s_nop 0
	global_load_lds_dwordx4 v[214:215], off
	s_waitcnt vmcnt(8)
	s_waitcnt lgkmcnt(0)
	s_barrier
	s_setprio 1
	s_waitcnt lgkmcnt(0)
	v_mfma_f32_16x16x32_bf16 v[60:63], v[150:153], v[182:185], v[60:63]
	v_mfma_f32_16x16x32_bf16 v[56:59], v[158:161], v[182:185], v[56:59]
	v_mfma_f32_16x16x32_bf16 v[44:47], v[150:153], v[190:193], v[44:47]
	v_mfma_f32_16x16x32_bf16 v[40:43], v[158:161], v[190:193], v[40:43]
	v_mfma_f32_16x16x32_bf16 v[28:31], v[150:153], v[198:201], v[28:31]
	v_mfma_f32_16x16x32_bf16 v[24:27], v[158:161], v[198:201], v[24:27]
	v_mfma_f32_16x16x32_bf16 v[12:15], v[150:153], v[206:209], v[12:15]
	v_mfma_f32_16x16x32_bf16 v[8:11], v[158:161], v[206:209], v[8:11]
	v_mfma_f32_16x16x32_bf16 v[60:63], v[154:157], v[186:189], v[60:63]
	v_mfma_f32_16x16x32_bf16 v[56:59], v[162:165], v[186:189], v[56:59]
	v_mfma_f32_16x16x32_bf16 v[44:47], v[154:157], v[194:197], v[44:47]
	v_mfma_f32_16x16x32_bf16 v[40:43], v[162:165], v[194:197], v[40:43]
	v_mfma_f32_16x16x32_bf16 v[28:31], v[154:157], v[202:205], v[28:31]
	v_mfma_f32_16x16x32_bf16 v[24:27], v[162:165], v[202:205], v[24:27]
	v_mfma_f32_16x16x32_bf16 v[12:15], v[154:157], v[210:213], v[12:15]
	v_mfma_f32_16x16x32_bf16 v[8:11], v[162:165], v[210:213], v[8:11]
	s_setprio 0
	s_setprio 1
	v_mfma_f32_16x16x32_bf16 v[52:55], v[166:169], v[182:185], v[52:55]
	v_mfma_f32_16x16x32_bf16 v[48:51], v[174:177], v[182:185], v[48:51]
	v_mfma_f32_16x16x32_bf16 v[36:39], v[166:169], v[190:193], v[36:39]
	v_mfma_f32_16x16x32_bf16 v[32:35], v[174:177], v[190:193], v[32:35]
	v_mfma_f32_16x16x32_bf16 v[20:23], v[166:169], v[198:201], v[20:23]
	v_mfma_f32_16x16x32_bf16 v[16:19], v[174:177], v[198:201], v[16:19]
	v_mfma_f32_16x16x32_bf16 v[4:7], v[166:169], v[206:209], v[4:7]
	v_mfma_f32_16x16x32_bf16 v[0:3], v[174:177], v[206:209], v[0:3]
	v_mfma_f32_16x16x32_bf16 v[52:55], v[170:173], v[186:189], v[52:55]
	v_mfma_f32_16x16x32_bf16 v[48:51], v[178:181], v[186:189], v[48:51]
	v_mfma_f32_16x16x32_bf16 v[36:39], v[170:173], v[194:197], v[36:39]
	v_mfma_f32_16x16x32_bf16 v[32:35], v[178:181], v[194:197], v[32:35]
	v_mfma_f32_16x16x32_bf16 v[20:23], v[170:173], v[202:205], v[20:23]
	v_mfma_f32_16x16x32_bf16 v[16:19], v[178:181], v[202:205], v[16:19]
	v_mfma_f32_16x16x32_bf16 v[4:7], v[170:173], v[210:213], v[4:7]
	v_mfma_f32_16x16x32_bf16 v[0:3], v[178:181], v[210:213], v[0:3]
	s_setprio 0
	s_barrier
	s_add_i32 s61, s61, 2
	s_add_u32 s36, s36, 0x100
	s_addc_u32 s37, s37, 0
	s_add_u32 s59, s59, 0x100
	s_addc_u32 s60, s60, 0
	s_cmp_eq_u32 s100, 0
	s_cbranch_scc1 .Ldhs8_idle6
	global_store_dwordx4 v255, v[250:253], s[16:17] offset:3072
.Ldhs8_done6:
	ds_read_b128 v[150:153], v147
	ds_read_b128 v[154:157], v147 offset:1024
	ds_read_b128 v[158:161], v147 offset:2048
	ds_read_b128 v[162:165], v147 offset:3072
	ds_read_b128 v[166:169], v148
	ds_read_b128 v[170:173], v148 offset:1024
	ds_read_b128 v[174:177], v148 offset:2048
	ds_read_b128 v[178:181], v148 offset:3072
	s_add_u32 s38, s36, 0xfffc0080
	s_addc_u32 s39, s37, -1
	s_cmp_eq_u32 s61, 12
	s_cselect_b32 s41, s27, s39
	s_cselect_b32 s40, s57, s38
	s_cselect_b32 s39, s25, s60
	s_cselect_b32 s38, s58, s59
	v_lshl_add_u64 v[214:215], s[36:37], 0, v[136:137]
	s_add_i32 m0, s35, 0xc000
	ds_read_b128 v[182:185], v149
	ds_read_b128 v[186:189], v149 offset:1024
	ds_read_b128 v[190:193], v149 offset:2048
	ds_read_b128 v[194:197], v149 offset:3072
	ds_read_b128 v[198:201], v149 offset:4096
	ds_read_b128 v[202:205], v149 offset:5120
	ds_read_b128 v[206:209], v149 offset:6144
	ds_read_b128 v[210:213], v149 offset:7168
	global_load_lds_dwordx4 v[214:215], off
	v_lshl_add_u64 v[214:215], s[36:37], 0, v[138:139]
	s_add_i32 m0, s35, 0xe000
	s_nop 0
	global_load_lds_dwordx4 v[214:215], off
	s_waitcnt vmcnt(9)
	s_waitcnt lgkmcnt(0)
	s_barrier
	s_setprio 1
	s_waitcnt lgkmcnt(0)
	v_mfma_f32_16x16x32_bf16 v[124:127], v[150:153], v[182:185], v[124:127]
	v_mfma_f32_16x16x32_bf16 v[120:123], v[158:161], v[182:185], v[120:123]
	v_mfma_f32_16x16x32_bf16 v[108:111], v[150:153], v[190:193], v[108:111]
	v_mfma_f32_16x16x32_bf16 v[104:107], v[158:161], v[190:193], v[104:107]
	v_mfma_f32_16x16x32_bf16 v[92:95], v[150:153], v[198:201], v[92:95]
	v_mfma_f32_16x16x32_bf16 v[88:91], v[158:161], v[198:201], v[88:91]
	v_mfma_f32_16x16x32_bf16 v[76:79], v[150:153], v[206:209], v[76:79]
	v_mfma_f32_16x16x32_bf16 v[72:75], v[158:161], v[206:209], v[72:75]
	v_mfma_f32_16x16x32_bf16 v[124:127], v[154:157], v[186:189], v[124:127]
	v_mfma_f32_16x16x32_bf16 v[120:123], v[162:165], v[186:189], v[120:123]
	v_mfma_f32_16x16x32_bf16 v[108:111], v[154:157], v[194:197], v[108:111]
	v_mfma_f32_16x16x32_bf16 v[104:107], v[162:165], v[194:197], v[104:107]
	v_mfma_f32_16x16x32_bf16 v[92:95], v[154:157], v[202:205], v[92:95]
	v_mfma_f32_16x16x32_bf16 v[88:91], v[162:165], v[202:205], v[88:91]
	v_mfma_f32_16x16x32_bf16 v[76:79], v[154:157], v[210:213], v[76:79]
	v_mfma_f32_16x16x32_bf16 v[72:75], v[162:165], v[210:213], v[72:75]
	s_setprio 0
	s_setprio 1
	v_mfma_f32_16x16x32_bf16 v[116:119], v[166:169], v[182:185], v[116:119]
	v_mfma_f32_16x16x32_bf16 v[112:115], v[174:177], v[182:185], v[112:115]
	v_mfma_f32_16x16x32_bf16 v[100:103], v[166:169], v[190:193], v[100:103]
	v_mfma_f32_16x16x32_bf16 v[96:99], v[174:177], v[190:193], v[96:99]
	v_mfma_f32_16x16x32_bf16 v[84:87], v[166:169], v[198:201], v[84:87]
	v_mfma_f32_16x16x32_bf16 v[80:83], v[174:177], v[198:201], v[80:83]
	v_mfma_f32_16x16x32_bf16 v[68:71], v[166:169], v[206:209], v[68:71]
	v_mfma_f32_16x16x32_bf16 v[64:67], v[174:177], v[206:209], v[64:67]
	v_mfma_f32_16x16x32_bf16 v[116:119], v[170:173], v[186:189], v[116:119]
	v_mfma_f32_16x16x32_bf16 v[112:115], v[178:181], v[186:189], v[112:115]
	v_mfma_f32_16x16x32_bf16 v[100:103], v[170:173], v[194:197], v[100:103]
	v_mfma_f32_16x16x32_bf16 v[96:99], v[178:181], v[194:197], v[96:99]
	v_mfma_f32_16x16x32_bf16 v[84:87], v[170:173], v[202:205], v[84:87]
	v_mfma_f32_16x16x32_bf16 v[80:83], v[178:181], v[202:205], v[80:83]
	v_mfma_f32_16x16x32_bf16 v[68:71], v[170:173], v[210:213], v[68:71]
	v_mfma_f32_16x16x32_bf16 v[64:67], v[178:181], v[210:213], v[64:67]
	s_setprio 0
	s_barrier
	s_add_i32 s62, s50, s3
	v_lshl_add_u64 v[214:215], s[38:39], 0, v[130:131]
	s_mov_b32 m0, s62
	ds_read_b128 v[182:185], v149 offset:16384
	ds_read_b128 v[186:189], v149 offset:17408
	ds_read_b128 v[190:193], v149 offset:18432
	ds_read_b128 v[194:197], v149 offset:19456
	ds_read_b128 v[198:201], v149 offset:20480
	ds_read_b128 v[202:205], v149 offset:21504
	ds_read_b128 v[206:209], v149 offset:22528
	ds_read_b128 v[210:213], v149 offset:23552
	global_load_lds_dwordx4 v[214:215], off
	s_add_i32 m0, s62, 0x2000
	s_add_u32 s62, s38, 0x40000
	v_lshl_add_u64 v[216:217], s[38:39], 0, v[134:135]
	s_addc_u32 s63, s39, 0
	s_add_i32 s64, s51, s3
	global_load_lds_dwordx4 v[216:217], off
	v_lshl_add_u64 v[218:219], s[62:63], 0, v[130:131]
	s_mov_b32 m0, s64
	v_lshl_add_u64 v[222:223], s[40:41], 0, v[132:133]
	global_load_lds_dwordx4 v[218:219], off
	v_lshl_add_u64 v[218:219], s[62:63], 0, v[134:135]
	s_add_i32 m0, s64, 0x2000
	s_nop 0
	global_load_lds_dwordx4 v[218:219], off
	v_lshl_add_u64 v[218:219], s[40:41], 0, v[128:129]
	s_mov_b32 m0, s35
	s_nop 0
	global_load_lds_dwordx4 v[218:219], off
	s_mov_b32 m0, s42
	s_nop 0
	global_load_lds_dwordx4 v[222:223], off
	s_waitcnt vmcnt(9)
	s_waitcnt lgkmcnt(0)
	s_barrier
	s_setprio 1
	s_waitcnt lgkmcnt(0)
	v_mfma_f32_16x16x32_bf16 v[60:63], v[150:153], v[182:185], v[60:63]
	v_mfma_f32_16x16x32_bf16 v[56:59], v[158:161], v[182:185], v[56:59]
	v_mfma_f32_16x16x32_bf16 v[44:47], v[150:153], v[190:193], v[44:47]
	v_mfma_f32_16x16x32_bf16 v[40:43], v[158:161], v[190:193], v[40:43]
	v_mfma_f32_16x16x32_bf16 v[28:31], v[150:153], v[198:201], v[28:31]
	v_mfma_f32_16x16x32_bf16 v[24:27], v[158:161], v[198:201], v[24:27]
	v_mfma_f32_16x16x32_bf16 v[12:15], v[150:153], v[206:209], v[12:15]
	v_mfma_f32_16x16x32_bf16 v[8:11], v[158:161], v[206:209], v[8:11]
	v_mfma_f32_16x16x32_bf16 v[60:63], v[154:157], v[186:189], v[60:63]
	v_mfma_f32_16x16x32_bf16 v[56:59], v[162:165], v[186:189], v[56:59]
	v_mfma_f32_16x16x32_bf16 v[44:47], v[154:157], v[194:197], v[44:47]
	v_mfma_f32_16x16x32_bf16 v[40:43], v[162:165], v[194:197], v[40:43]
	v_mfma_f32_16x16x32_bf16 v[28:31], v[154:157], v[202:205], v[28:31]
	v_mfma_f32_16x16x32_bf16 v[24:27], v[162:165], v[202:205], v[24:27]
	v_mfma_f32_16x16x32_bf16 v[12:15], v[154:157], v[210:213], v[12:15]
	v_mfma_f32_16x16x32_bf16 v[8:11], v[162:165], v[210:213], v[8:11]
	s_setprio 0
	s_setprio 1
	v_mfma_f32_16x16x32_bf16 v[52:55], v[166:169], v[182:185], v[52:55]
	v_mfma_f32_16x16x32_bf16 v[48:51], v[174:177], v[182:185], v[48:51]
	v_mfma_f32_16x16x32_bf16 v[36:39], v[166:169], v[190:193], v[36:39]
	v_mfma_f32_16x16x32_bf16 v[32:35], v[174:177], v[190:193], v[32:35]
	v_mfma_f32_16x16x32_bf16 v[20:23], v[166:169], v[198:201], v[20:23]
	v_mfma_f32_16x16x32_bf16 v[16:19], v[174:177], v[198:201], v[16:19]
	v_mfma_f32_16x16x32_bf16 v[4:7], v[166:169], v[206:209], v[4:7]
	v_mfma_f32_16x16x32_bf16 v[0:3], v[174:177], v[206:209], v[0:3]
	v_mfma_f32_16x16x32_bf16 v[52:55], v[170:173], v[186:189], v[52:55]
	v_mfma_f32_16x16x32_bf16 v[48:51], v[178:181], v[186:189], v[48:51]
	v_mfma_f32_16x16x32_bf16 v[36:39], v[170:173], v[194:197], v[36:39]
	v_mfma_f32_16x16x32_bf16 v[32:35], v[178:181], v[194:197], v[32:35]
	v_mfma_f32_16x16x32_bf16 v[20:23], v[170:173], v[202:205], v[20:23]
	v_mfma_f32_16x16x32_bf16 v[16:19], v[178:181], v[202:205], v[16:19]
	v_mfma_f32_16x16x32_bf16 v[4:7], v[170:173], v[210:213], v[4:7]
	v_mfma_f32_16x16x32_bf16 v[0:3], v[178:181], v[210:213], v[0:3]
	s_setprio 0
	s_barrier
	s_add_i32 s62, 0, 0x18000
	s_add_i32 s63, 0, 0x1c000
	v_add_u32_e32 v162, s62, v145
	v_add_u32_e32 v178, s63, v145
	ds_read_b128 v[150:153], v162
	ds_read_b128 v[154:157], v162 offset:1024
	ds_read_b128 v[158:161], v162 offset:2048
	ds_read_b128 v[162:165], v162 offset:3072
	ds_read_b128 v[166:169], v178
	ds_read_b128 v[170:173], v178 offset:1024
	ds_read_b128 v[174:177], v178 offset:2048
	ds_read_b128 v[178:181], v178 offset:3072
	s_add_u32 s40, s40, 0x40000
	s_addc_u32 s41, s41, 0
	s_mov_b32 m0, s43
	v_lshl_add_u64 v[224:225], s[40:41], 0, v[128:129]
	ds_read_b128 v[182:185], v149 offset:32768
	ds_read_b128 v[186:189], v149 offset:33792
	ds_read_b128 v[190:193], v149 offset:34816
	ds_read_b128 v[194:197], v149 offset:35840
	ds_read_b128 v[198:201], v149 offset:36864
	ds_read_b128 v[202:205], v149 offset:37888
	ds_read_b128 v[206:209], v149 offset:38912
	ds_read_b128 v[210:213], v149 offset:39936
	global_load_lds_dwordx4 v[224:225], off
	v_lshl_add_u64 v[224:225], s[40:41], 0, v[132:133]
	s_mov_b32 m0, s44
	s_nop 0
	global_load_lds_dwordx4 v[224:225], off
	s_waitcnt vmcnt(8)
	s_waitcnt lgkmcnt(0)
	s_barrier
	s_setprio 1
	s_waitcnt lgkmcnt(0)
	v_mfma_f32_16x16x32_bf16 v[124:127], v[150:153], v[182:185], v[124:127]
	v_mfma_f32_16x16x32_bf16 v[120:123], v[158:161], v[182:185], v[120:123]
	v_mfma_f32_16x16x32_bf16 v[108:111], v[150:153], v[190:193], v[108:111]
	v_mfma_f32_16x16x32_bf16 v[104:107], v[158:161], v[190:193], v[104:107]
	v_mfma_f32_16x16x32_bf16 v[92:95], v[150:153], v[198:201], v[92:95]
	v_mfma_f32_16x16x32_bf16 v[88:91], v[158:161], v[198:201], v[88:91]
	v_mfma_f32_16x16x32_bf16 v[76:79], v[150:153], v[206:209], v[76:79]
	v_mfma_f32_16x16x32_bf16 v[72:75], v[158:161], v[206:209], v[72:75]
	v_mfma_f32_16x16x32_bf16 v[124:127], v[154:157], v[186:189], v[124:127]
	v_mfma_f32_16x16x32_bf16 v[120:123], v[162:165], v[186:189], v[120:123]
	v_mfma_f32_16x16x32_bf16 v[108:111], v[154:157], v[194:197], v[108:111]
	v_mfma_f32_16x16x32_bf16 v[104:107], v[162:165], v[194:197], v[104:107]
	v_mfma_f32_16x16x32_bf16 v[92:95], v[154:157], v[202:205], v[92:95]
	v_mfma_f32_16x16x32_bf16 v[88:91], v[162:165], v[202:205], v[88:91]
	v_mfma_f32_16x16x32_bf16 v[76:79], v[154:157], v[210:213], v[76:79]
	v_mfma_f32_16x16x32_bf16 v[72:75], v[162:165], v[210:213], v[72:75]
	s_setprio 0
	s_setprio 1
	v_mfma_f32_16x16x32_bf16 v[116:119], v[166:169], v[182:185], v[116:119]
	v_mfma_f32_16x16x32_bf16 v[112:115], v[174:177], v[182:185], v[112:115]
	v_mfma_f32_16x16x32_bf16 v[100:103], v[166:169], v[190:193], v[100:103]
	v_mfma_f32_16x16x32_bf16 v[96:99], v[174:177], v[190:193], v[96:99]
	v_mfma_f32_16x16x32_bf16 v[84:87], v[166:169], v[198:201], v[84:87]
	v_mfma_f32_16x16x32_bf16 v[80:83], v[174:177], v[198:201], v[80:83]
	v_mfma_f32_16x16x32_bf16 v[68:71], v[166:169], v[206:209], v[68:71]
	v_mfma_f32_16x16x32_bf16 v[64:67], v[174:177], v[206:209], v[64:67]
	v_mfma_f32_16x16x32_bf16 v[116:119], v[170:173], v[186:189], v[116:119]
	v_mfma_f32_16x16x32_bf16 v[112:115], v[178:181], v[186:189], v[112:115]
	v_mfma_f32_16x16x32_bf16 v[100:103], v[170:173], v[194:197], v[100:103]
	v_mfma_f32_16x16x32_bf16 v[96:99], v[178:181], v[194:197], v[96:99]
	v_mfma_f32_16x16x32_bf16 v[84:87], v[170:173], v[202:205], v[84:87]
	v_mfma_f32_16x16x32_bf16 v[80:83], v[178:181], v[202:205], v[80:83]
	v_mfma_f32_16x16x32_bf16 v[68:71], v[170:173], v[210:213], v[68:71]
	v_mfma_f32_16x16x32_bf16 v[64:67], v[178:181], v[210:213], v[64:67]
	s_setprio 0
	s_barrier
	s_add_i32 s40, s62, s3
	v_lshl_add_u64 v[214:215], v[214:215], 0, s[12:13]
	s_mov_b32 m0, s40
	ds_read_b128 v[182:185], v149 offset:49152
	ds_read_b128 v[186:189], v149 offset:50176
	ds_read_b128 v[190:193], v149 offset:51200
	ds_read_b128 v[194:197], v149 offset:52224
	ds_read_b128 v[198:201], v149 offset:53248
	ds_read_b128 v[202:205], v149 offset:54272
	ds_read_b128 v[206:209], v149 offset:55296
	ds_read_b128 v[210:213], v149 offset:56320
	global_load_lds_dwordx4 v[214:215], off
	s_add_i32 m0, s40, 0x2000
	s_add_u32 s38, s38, 0x40080
	v_lshl_add_u64 v[214:215], v[216:217], 0, s[12:13]
	s_addc_u32 s39, s39, 0
	s_add_i32 s40, s63, s3
	global_load_lds_dwordx4 v[214:215], off
	v_lshl_add_u64 v[214:215], s[38:39], 0, v[130:131]
	s_mov_b32 m0, s40
	s_nop 0
	global_load_lds_dwordx4 v[214:215], off
	v_lshl_add_u64 v[214:215], s[38:39], 0, v[134:135]
	s_add_i32 m0, s40, 0x2000
	s_nop 0
	global_load_lds_dwordx4 v[214:215], off
	v_lshl_add_u64 v[214:215], v[218:219], 0, s[12:13]
	s_mov_b32 m0, s47
	s_nop 0
	global_load_lds_dwordx4 v[214:215], off
	v_lshl_add_u64 v[214:215], v[222:223], 0, s[12:13]
	s_mov_b32 m0, s48
	s_nop 0
	global_load_lds_dwordx4 v[214:215], off
	s_waitcnt vmcnt(8)
	s_waitcnt lgkmcnt(0)
	s_barrier
	s_setprio 1
	s_waitcnt lgkmcnt(0)
	v_mfma_f32_16x16x32_bf16 v[60:63], v[150:153], v[182:185], v[60:63]
	v_mfma_f32_16x16x32_bf16 v[56:59], v[158:161], v[182:185], v[56:59]
	v_mfma_f32_16x16x32_bf16 v[44:47], v[150:153], v[190:193], v[44:47]
	v_mfma_f32_16x16x32_bf16 v[40:43], v[158:161], v[190:193], v[40:43]
	v_mfma_f32_16x16x32_bf16 v[28:31], v[150:153], v[198:201], v[28:31]
	v_mfma_f32_16x16x32_bf16 v[24:27], v[158:161], v[198:201], v[24:27]
	v_mfma_f32_16x16x32_bf16 v[12:15], v[150:153], v[206:209], v[12:15]
	v_mfma_f32_16x16x32_bf16 v[8:11], v[158:161], v[206:209], v[8:11]
	v_mfma_f32_16x16x32_bf16 v[60:63], v[154:157], v[186:189], v[60:63]
	v_mfma_f32_16x16x32_bf16 v[56:59], v[162:165], v[186:189], v[56:59]
	v_mfma_f32_16x16x32_bf16 v[44:47], v[154:157], v[194:197], v[44:47]
	v_mfma_f32_16x16x32_bf16 v[40:43], v[162:165], v[194:197], v[40:43]
	v_mfma_f32_16x16x32_bf16 v[28:31], v[154:157], v[202:205], v[28:31]
	v_mfma_f32_16x16x32_bf16 v[24:27], v[162:165], v[202:205], v[24:27]
	v_mfma_f32_16x16x32_bf16 v[12:15], v[154:157], v[210:213], v[12:15]
	v_mfma_f32_16x16x32_bf16 v[8:11], v[162:165], v[210:213], v[8:11]
	s_setprio 0
	s_setprio 1
	v_mfma_f32_16x16x32_bf16 v[52:55], v[166:169], v[182:185], v[52:55]
	v_mfma_f32_16x16x32_bf16 v[48:51], v[174:177], v[182:185], v[48:51]
	v_mfma_f32_16x16x32_bf16 v[36:39], v[166:169], v[190:193], v[36:39]
	v_mfma_f32_16x16x32_bf16 v[32:35], v[174:177], v[190:193], v[32:35]
	v_mfma_f32_16x16x32_bf16 v[20:23], v[166:169], v[198:201], v[20:23]
	v_mfma_f32_16x16x32_bf16 v[16:19], v[174:177], v[198:201], v[16:19]
	v_mfma_f32_16x16x32_bf16 v[4:7], v[166:169], v[206:209], v[4:7]
	v_mfma_f32_16x16x32_bf16 v[0:3], v[174:177], v[206:209], v[0:3]
	v_mfma_f32_16x16x32_bf16 v[52:55], v[170:173], v[186:189], v[52:55]
	v_mfma_f32_16x16x32_bf16 v[48:51], v[178:181], v[186:189], v[48:51]
	v_mfma_f32_16x16x32_bf16 v[36:39], v[170:173], v[194:197], v[36:39]
	v_mfma_f32_16x16x32_bf16 v[32:35], v[178:181], v[194:197], v[32:35]
	v_mfma_f32_16x16x32_bf16 v[20:23], v[170:173], v[202:205], v[20:23]
	v_mfma_f32_16x16x32_bf16 v[16:19], v[178:181], v[202:205], v[16:19]
	v_mfma_f32_16x16x32_bf16 v[4:7], v[170:173], v[210:213], v[4:7]
	v_mfma_f32_16x16x32_bf16 v[0:3], v[178:181], v[210:213], v[0:3]
	s_setprio 0
	s_barrier
	s_add_i32 s61, s61, 2
	s_add_u32 s36, s36, 0x100
	s_addc_u32 s37, s37, 0
	s_add_u32 s59, s59, 0x100
	s_addc_u32 s60, s60, 0
	s_cmp_eq_u32 s100, 0
	s_cbranch_scc1 .Ldhs8_idle7
	global_store_dwordx4 v255, v[140:143], s[18:19] offset:3072
.Ldhs8_done7:
	ds_read_b128 v[150:153], v147
	ds_read_b128 v[154:157], v147 offset:1024
	ds_read_b128 v[158:161], v147 offset:2048
	ds_read_b128 v[162:165], v147 offset:3072
	ds_read_b128 v[166:169], v148
	ds_read_b128 v[170:173], v148 offset:1024
	ds_read_b128 v[174:177], v148 offset:2048
	ds_read_b128 v[178:181], v148 offset:3072
	s_add_u32 s38, s36, 0xfffc0080
	s_addc_u32 s39, s37, -1
	s_cmp_eq_u32 s61, 12
	s_cselect_b32 s41, s27, s39
	s_cselect_b32 s40, s57, s38
	s_cselect_b32 s39, s25, s60
	s_cselect_b32 s38, s58, s59
	v_lshl_add_u64 v[214:215], s[36:37], 0, v[136:137]
	s_add_i32 m0, s35, 0xc000
	ds_read_b128 v[182:185], v149
	ds_read_b128 v[186:189], v149 offset:1024
	ds_read_b128 v[190:193], v149 offset:2048
	ds_read_b128 v[194:197], v149 offset:3072
	ds_read_b128 v[198:201], v149 offset:4096
	ds_read_b128 v[202:205], v149 offset:5120
	ds_read_b128 v[206:209], v149 offset:6144
	ds_read_b128 v[210:213], v149 offset:7168
	global_load_lds_dwordx4 v[214:215], off
	v_lshl_add_u64 v[214:215], s[36:37], 0, v[138:139]
	s_add_i32 m0, s35, 0xe000
	s_nop 0
	global_load_lds_dwordx4 v[214:215], off
	s_waitcnt vmcnt(9)
	s_waitcnt lgkmcnt(0)
	s_barrier
	s_setprio 1
	s_waitcnt lgkmcnt(0)
	v_mfma_f32_16x16x32_bf16 v[124:127], v[150:153], v[182:185], v[124:127]
	v_mfma_f32_16x16x32_bf16 v[120:123], v[158:161], v[182:185], v[120:123]
	v_mfma_f32_16x16x32_bf16 v[108:111], v[150:153], v[190:193], v[108:111]
	v_mfma_f32_16x16x32_bf16 v[104:107], v[158:161], v[190:193], v[104:107]
	v_mfma_f32_16x16x32_bf16 v[92:95], v[150:153], v[198:201], v[92:95]
	v_mfma_f32_16x16x32_bf16 v[88:91], v[158:161], v[198:201], v[88:91]
	v_mfma_f32_16x16x32_bf16 v[76:79], v[150:153], v[206:209], v[76:79]
	v_mfma_f32_16x16x32_bf16 v[72:75], v[158:161], v[206:209], v[72:75]
	v_mfma_f32_16x16x32_bf16 v[124:127], v[154:157], v[186:189], v[124:127]
	v_mfma_f32_16x16x32_bf16 v[120:123], v[162:165], v[186:189], v[120:123]
	v_mfma_f32_16x16x32_bf16 v[108:111], v[154:157], v[194:197], v[108:111]
	v_mfma_f32_16x16x32_bf16 v[104:107], v[162:165], v[194:197], v[104:107]
	v_mfma_f32_16x16x32_bf16 v[92:95], v[154:157], v[202:205], v[92:95]
	v_mfma_f32_16x16x32_bf16 v[88:91], v[162:165], v[202:205], v[88:91]
	v_mfma_f32_16x16x32_bf16 v[76:79], v[154:157], v[210:213], v[76:79]
	v_mfma_f32_16x16x32_bf16 v[72:75], v[162:165], v[210:213], v[72:75]
	s_setprio 0
	s_setprio 1
	v_mfma_f32_16x16x32_bf16 v[116:119], v[166:169], v[182:185], v[116:119]
	v_mfma_f32_16x16x32_bf16 v[112:115], v[174:177], v[182:185], v[112:115]
	v_mfma_f32_16x16x32_bf16 v[100:103], v[166:169], v[190:193], v[100:103]
	v_mfma_f32_16x16x32_bf16 v[96:99], v[174:177], v[190:193], v[96:99]
	v_mfma_f32_16x16x32_bf16 v[84:87], v[166:169], v[198:201], v[84:87]
	v_mfma_f32_16x16x32_bf16 v[80:83], v[174:177], v[198:201], v[80:83]
	v_mfma_f32_16x16x32_bf16 v[68:71], v[166:169], v[206:209], v[68:71]
	v_mfma_f32_16x16x32_bf16 v[64:67], v[174:177], v[206:209], v[64:67]
	v_mfma_f32_16x16x32_bf16 v[116:119], v[170:173], v[186:189], v[116:119]
	v_mfma_f32_16x16x32_bf16 v[112:115], v[178:181], v[186:189], v[112:115]
	v_mfma_f32_16x16x32_bf16 v[100:103], v[170:173], v[194:197], v[100:103]
	v_mfma_f32_16x16x32_bf16 v[96:99], v[178:181], v[194:197], v[96:99]
	v_mfma_f32_16x16x32_bf16 v[84:87], v[170:173], v[202:205], v[84:87]
	v_mfma_f32_16x16x32_bf16 v[80:83], v[178:181], v[202:205], v[80:83]
	v_mfma_f32_16x16x32_bf16 v[68:71], v[170:173], v[210:213], v[68:71]
	v_mfma_f32_16x16x32_bf16 v[64:67], v[178:181], v[210:213], v[64:67]
	s_setprio 0
	s_barrier
	s_add_i32 s62, s50, s3
	v_lshl_add_u64 v[214:215], s[38:39], 0, v[130:131]
	s_mov_b32 m0, s62
	ds_read_b128 v[182:185], v149 offset:16384
	ds_read_b128 v[186:189], v149 offset:17408
	ds_read_b128 v[190:193], v149 offset:18432
	ds_read_b128 v[194:197], v149 offset:19456
	ds_read_b128 v[198:201], v149 offset:20480
	ds_read_b128 v[202:205], v149 offset:21504
	ds_read_b128 v[206:209], v149 offset:22528
	ds_read_b128 v[210:213], v149 offset:23552
	global_load_lds_dwordx4 v[214:215], off
	s_add_i32 m0, s62, 0x2000
	s_add_u32 s62, s38, 0x40000
	v_lshl_add_u64 v[216:217], s[38:39], 0, v[134:135]
	s_addc_u32 s63, s39, 0
	s_add_i32 s64, s51, s3
	global_load_lds_dwordx4 v[216:217], off
	v_lshl_add_u64 v[218:219], s[62:63], 0, v[130:131]
	s_mov_b32 m0, s64
	v_lshl_add_u64 v[222:223], s[40:41], 0, v[132:133]
	global_load_lds_dwordx4 v[218:219], off
	v_lshl_add_u64 v[218:219], s[62:63], 0, v[134:135]
	s_add_i32 m0, s64, 0x2000
	s_nop 0
	global_load_lds_dwordx4 v[218:219], off
	v_lshl_add_u64 v[218:219], s[40:41], 0, v[128:129]
	s_mov_b32 m0, s35
	s_nop 0
	global_load_lds_dwordx4 v[218:219], off
	s_mov_b32 m0, s42
	s_nop 0
	global_load_lds_dwordx4 v[222:223], off
	s_waitcnt vmcnt(9)
	s_waitcnt lgkmcnt(0)
	s_barrier
	s_setprio 1
	s_waitcnt lgkmcnt(0)
	v_mfma_f32_16x16x32_bf16 v[60:63], v[150:153], v[182:185], v[60:63]
	v_mfma_f32_16x16x32_bf16 v[56:59], v[158:161], v[182:185], v[56:59]
	v_mfma_f32_16x16x32_bf16 v[44:47], v[150:153], v[190:193], v[44:47]
	v_mfma_f32_16x16x32_bf16 v[40:43], v[158:161], v[190:193], v[40:43]
	v_mfma_f32_16x16x32_bf16 v[28:31], v[150:153], v[198:201], v[28:31]
	v_mfma_f32_16x16x32_bf16 v[24:27], v[158:161], v[198:201], v[24:27]
	v_mfma_f32_16x16x32_bf16 v[12:15], v[150:153], v[206:209], v[12:15]
	v_mfma_f32_16x16x32_bf16 v[8:11], v[158:161], v[206:209], v[8:11]
	v_mfma_f32_16x16x32_bf16 v[60:63], v[154:157], v[186:189], v[60:63]
	v_mfma_f32_16x16x32_bf16 v[56:59], v[162:165], v[186:189], v[56:59]
	v_mfma_f32_16x16x32_bf16 v[44:47], v[154:157], v[194:197], v[44:47]
	v_mfma_f32_16x16x32_bf16 v[40:43], v[162:165], v[194:197], v[40:43]
	v_mfma_f32_16x16x32_bf16 v[28:31], v[154:157], v[202:205], v[28:31]
	v_mfma_f32_16x16x32_bf16 v[24:27], v[162:165], v[202:205], v[24:27]
	v_mfma_f32_16x16x32_bf16 v[12:15], v[154:157], v[210:213], v[12:15]
	v_mfma_f32_16x16x32_bf16 v[8:11], v[162:165], v[210:213], v[8:11]
	s_setprio 0
	s_setprio 1
	v_mfma_f32_16x16x32_bf16 v[52:55], v[166:169], v[182:185], v[52:55]
	v_mfma_f32_16x16x32_bf16 v[48:51], v[174:177], v[182:185], v[48:51]
	v_mfma_f32_16x16x32_bf16 v[36:39], v[166:169], v[190:193], v[36:39]
	v_mfma_f32_16x16x32_bf16 v[32:35], v[174:177], v[190:193], v[32:35]
	v_mfma_f32_16x16x32_bf16 v[20:23], v[166:169], v[198:201], v[20:23]
	v_mfma_f32_16x16x32_bf16 v[16:19], v[174:177], v[198:201], v[16:19]
	v_mfma_f32_16x16x32_bf16 v[4:7], v[166:169], v[206:209], v[4:7]
	v_mfma_f32_16x16x32_bf16 v[0:3], v[174:177], v[206:209], v[0:3]
	v_mfma_f32_16x16x32_bf16 v[52:55], v[170:173], v[186:189], v[52:55]
	v_mfma_f32_16x16x32_bf16 v[48:51], v[178:181], v[186:189], v[48:51]
	v_mfma_f32_16x16x32_bf16 v[36:39], v[170:173], v[194:197], v[36:39]
	v_mfma_f32_16x16x32_bf16 v[32:35], v[178:181], v[194:197], v[32:35]
	v_mfma_f32_16x16x32_bf16 v[20:23], v[170:173], v[202:205], v[20:23]
	v_mfma_f32_16x16x32_bf16 v[16:19], v[178:181], v[202:205], v[16:19]
	v_mfma_f32_16x16x32_bf16 v[4:7], v[170:173], v[210:213], v[4:7]
	v_mfma_f32_16x16x32_bf16 v[0:3], v[178:181], v[210:213], v[0:3]
	s_setprio 0
	s_barrier
	s_add_i32 s62, 0, 0x18000
	s_add_i32 s63, 0, 0x1c000
	v_add_u32_e32 v162, s62, v145
	v_add_u32_e32 v178, s63, v145
	ds_read_b128 v[150:153], v162
	ds_read_b128 v[154:157], v162 offset:1024
	ds_read_b128 v[158:161], v162 offset:2048
	ds_read_b128 v[162:165], v162 offset:3072
	ds_read_b128 v[166:169], v178
	ds_read_b128 v[170:173], v178 offset:1024
	ds_read_b128 v[174:177], v178 offset:2048
	ds_read_b128 v[178:181], v178 offset:3072
	s_add_u32 s40, s40, 0x40000
	s_addc_u32 s41, s41, 0
	s_mov_b32 m0, s43
	v_lshl_add_u64 v[224:225], s[40:41], 0, v[128:129]
	ds_read_b128 v[182:185], v149 offset:32768
	ds_read_b128 v[186:189], v149 offset:33792
	ds_read_b128 v[190:193], v149 offset:34816
	ds_read_b128 v[194:197], v149 offset:35840
	ds_read_b128 v[198:201], v149 offset:36864
	ds_read_b128 v[202:205], v149 offset:37888
	ds_read_b128 v[206:209], v149 offset:38912
	ds_read_b128 v[210:213], v149 offset:39936
	global_load_lds_dwordx4 v[224:225], off
	v_lshl_add_u64 v[224:225], s[40:41], 0, v[132:133]
	s_mov_b32 m0, s44
	s_nop 0
	global_load_lds_dwordx4 v[224:225], off
	s_waitcnt vmcnt(8)
	s_waitcnt lgkmcnt(0)
	s_barrier
	s_setprio 1
	s_waitcnt lgkmcnt(0)
	v_mfma_f32_16x16x32_bf16 v[124:127], v[150:153], v[182:185], v[124:127]
	v_mfma_f32_16x16x32_bf16 v[120:123], v[158:161], v[182:185], v[120:123]
	v_mfma_f32_16x16x32_bf16 v[108:111], v[150:153], v[190:193], v[108:111]
	v_mfma_f32_16x16x32_bf16 v[104:107], v[158:161], v[190:193], v[104:107]
	v_mfma_f32_16x16x32_bf16 v[92:95], v[150:153], v[198:201], v[92:95]
	v_mfma_f32_16x16x32_bf16 v[88:91], v[158:161], v[198:201], v[88:91]
	v_mfma_f32_16x16x32_bf16 v[76:79], v[150:153], v[206:209], v[76:79]
	v_mfma_f32_16x16x32_bf16 v[72:75], v[158:161], v[206:209], v[72:75]
	v_mfma_f32_16x16x32_bf16 v[124:127], v[154:157], v[186:189], v[124:127]
	v_mfma_f32_16x16x32_bf16 v[120:123], v[162:165], v[186:189], v[120:123]
	v_mfma_f32_16x16x32_bf16 v[108:111], v[154:157], v[194:197], v[108:111]
	v_mfma_f32_16x16x32_bf16 v[104:107], v[162:165], v[194:197], v[104:107]
	v_mfma_f32_16x16x32_bf16 v[92:95], v[154:157], v[202:205], v[92:95]
	v_mfma_f32_16x16x32_bf16 v[88:91], v[162:165], v[202:205], v[88:91]
	v_mfma_f32_16x16x32_bf16 v[76:79], v[154:157], v[210:213], v[76:79]
	v_mfma_f32_16x16x32_bf16 v[72:75], v[162:165], v[210:213], v[72:75]
	s_setprio 0
	s_setprio 1
	v_mfma_f32_16x16x32_bf16 v[116:119], v[166:169], v[182:185], v[116:119]
	v_mfma_f32_16x16x32_bf16 v[112:115], v[174:177], v[182:185], v[112:115]
	v_mfma_f32_16x16x32_bf16 v[100:103], v[166:169], v[190:193], v[100:103]
	v_mfma_f32_16x16x32_bf16 v[96:99], v[174:177], v[190:193], v[96:99]
	v_mfma_f32_16x16x32_bf16 v[84:87], v[166:169], v[198:201], v[84:87]
	v_mfma_f32_16x16x32_bf16 v[80:83], v[174:177], v[198:201], v[80:83]
	v_mfma_f32_16x16x32_bf16 v[68:71], v[166:169], v[206:209], v[68:71]
	v_mfma_f32_16x16x32_bf16 v[64:67], v[174:177], v[206:209], v[64:67]
	v_mfma_f32_16x16x32_bf16 v[116:119], v[170:173], v[186:189], v[116:119]
	v_mfma_f32_16x16x32_bf16 v[112:115], v[178:181], v[186:189], v[112:115]
	v_mfma_f32_16x16x32_bf16 v[100:103], v[170:173], v[194:197], v[100:103]
	v_mfma_f32_16x16x32_bf16 v[96:99], v[178:181], v[194:197], v[96:99]
	v_mfma_f32_16x16x32_bf16 v[84:87], v[170:173], v[202:205], v[84:87]
	v_mfma_f32_16x16x32_bf16 v[80:83], v[178:181], v[202:205], v[80:83]
	v_mfma_f32_16x16x32_bf16 v[68:71], v[170:173], v[210:213], v[68:71]
	v_mfma_f32_16x16x32_bf16 v[64:67], v[178:181], v[210:213], v[64:67]
	s_setprio 0
	s_barrier
	s_add_i32 s40, s62, s3
	v_lshl_add_u64 v[214:215], v[214:215], 0, s[12:13]
	s_mov_b32 m0, s40
	ds_read_b128 v[182:185], v149 offset:49152
	ds_read_b128 v[186:189], v149 offset:50176
	ds_read_b128 v[190:193], v149 offset:51200
	ds_read_b128 v[194:197], v149 offset:52224
	ds_read_b128 v[198:201], v149 offset:53248
	ds_read_b128 v[202:205], v149 offset:54272
	ds_read_b128 v[206:209], v149 offset:55296
	ds_read_b128 v[210:213], v149 offset:56320
	global_load_lds_dwordx4 v[214:215], off
	s_add_i32 m0, s40, 0x2000
	s_add_u32 s38, s38, 0x40080
	v_lshl_add_u64 v[214:215], v[216:217], 0, s[12:13]
	s_addc_u32 s39, s39, 0
	s_add_i32 s40, s63, s3
	global_load_lds_dwordx4 v[214:215], off
	v_lshl_add_u64 v[214:215], s[38:39], 0, v[130:131]
	s_mov_b32 m0, s40
	s_nop 0
	global_load_lds_dwordx4 v[214:215], off
	v_lshl_add_u64 v[214:215], s[38:39], 0, v[134:135]
	s_add_i32 m0, s40, 0x2000
	s_nop 0
	global_load_lds_dwordx4 v[214:215], off
	v_lshl_add_u64 v[214:215], v[218:219], 0, s[12:13]
	s_mov_b32 m0, s47
	s_nop 0
	global_load_lds_dwordx4 v[214:215], off
	v_lshl_add_u64 v[214:215], v[222:223], 0, s[12:13]
	s_mov_b32 m0, s48
	s_nop 0
	global_load_lds_dwordx4 v[214:215], off
	s_waitcnt vmcnt(8)
	s_waitcnt lgkmcnt(0)
	s_barrier
	s_setprio 1
	s_waitcnt lgkmcnt(0)
	v_mfma_f32_16x16x32_bf16 v[60:63], v[150:153], v[182:185], v[60:63]
	v_mfma_f32_16x16x32_bf16 v[56:59], v[158:161], v[182:185], v[56:59]
	v_mfma_f32_16x16x32_bf16 v[44:47], v[150:153], v[190:193], v[44:47]
	v_mfma_f32_16x16x32_bf16 v[40:43], v[158:161], v[190:193], v[40:43]
	v_mfma_f32_16x16x32_bf16 v[28:31], v[150:153], v[198:201], v[28:31]
	v_mfma_f32_16x16x32_bf16 v[24:27], v[158:161], v[198:201], v[24:27]
	v_mfma_f32_16x16x32_bf16 v[12:15], v[150:153], v[206:209], v[12:15]
	v_mfma_f32_16x16x32_bf16 v[8:11], v[158:161], v[206:209], v[8:11]
	v_mfma_f32_16x16x32_bf16 v[60:63], v[154:157], v[186:189], v[60:63]
	v_mfma_f32_16x16x32_bf16 v[56:59], v[162:165], v[186:189], v[56:59]
	v_mfma_f32_16x16x32_bf16 v[44:47], v[154:157], v[194:197], v[44:47]
	v_mfma_f32_16x16x32_bf16 v[40:43], v[162:165], v[194:197], v[40:43]
	v_mfma_f32_16x16x32_bf16 v[28:31], v[154:157], v[202:205], v[28:31]
	v_mfma_f32_16x16x32_bf16 v[24:27], v[162:165], v[202:205], v[24:27]
	v_mfma_f32_16x16x32_bf16 v[12:15], v[154:157], v[210:213], v[12:15]
	v_mfma_f32_16x16x32_bf16 v[8:11], v[162:165], v[210:213], v[8:11]
	s_setprio 0
	s_setprio 1
	v_mfma_f32_16x16x32_bf16 v[52:55], v[166:169], v[182:185], v[52:55]
	v_mfma_f32_16x16x32_bf16 v[48:51], v[174:177], v[182:185], v[48:51]
	v_mfma_f32_16x16x32_bf16 v[36:39], v[166:169], v[190:193], v[36:39]
	v_mfma_f32_16x16x32_bf16 v[32:35], v[174:177], v[190:193], v[32:35]
	v_mfma_f32_16x16x32_bf16 v[20:23], v[166:169], v[198:201], v[20:23]
	v_mfma_f32_16x16x32_bf16 v[16:19], v[174:177], v[198:201], v[16:19]
	v_mfma_f32_16x16x32_bf16 v[4:7], v[166:169], v[206:209], v[4:7]
	v_mfma_f32_16x16x32_bf16 v[0:3], v[174:177], v[206:209], v[0:3]
	v_mfma_f32_16x16x32_bf16 v[52:55], v[170:173], v[186:189], v[52:55]
	v_mfma_f32_16x16x32_bf16 v[48:51], v[178:181], v[186:189], v[48:51]
	v_mfma_f32_16x16x32_bf16 v[36:39], v[170:173], v[194:197], v[36:39]
	v_mfma_f32_16x16x32_bf16 v[32:35], v[178:181], v[194:197], v[32:35]
	v_mfma_f32_16x16x32_bf16 v[20:23], v[170:173], v[202:205], v[20:23]
	v_mfma_f32_16x16x32_bf16 v[16:19], v[178:181], v[202:205], v[16:19]
	v_mfma_f32_16x16x32_bf16 v[4:7], v[170:173], v[210:213], v[4:7]
	v_mfma_f32_16x16x32_bf16 v[0:3], v[178:181], v[210:213], v[0:3]
	s_setprio 0
	s_barrier
	s_add_i32 s61, s61, 2
	s_add_u32 s36, s36, 0x100
	s_addc_u32 s37, s37, 0
	s_add_u32 s59, s59, 0x100
	s_addc_u32 s60, s60, 0
	s_and_b64 vcc, exec, s[14:15]
	s_cbranch_vccz .LBB0_880
	s_barrier

.Ldhs8_idle0:
	global_load_ubyte v255, v221, s[16:17]
	s_branch .Ldhs8_done0
